# attention: epilogue gate loads issued two tail steps earlier into free VGPRs, copied in the epilogue; on top of v55
# baseline (speedup 1.0000x reference)
; __device__ __forceinline__ int crow(int r,int hi){return (r&3)+8*(r>>2)+4*hi;}
; __device__ __forceinline__ unsigned cvtpk_s(float lo,float hi){f32x2_t v={lo,hi};bf16x2_t b=__builtin_convertvector(v,bf16x2_t);return __builtin_bit_cast(unsigned,b);}
;       #define SILU_(x) ((x)*__builtin_amdgcn_rcpf(1.f+__builtin_amdgcn_exp2f(-1.4426950408889634f*(x))))
; __device__ __forceinline__ int crow(int g, int hi) { return (g & 3) + 8 * (g >> 2) + 4 * hi; }
; #define SILU_(x) ((x) * __builtin_amdgcn_rcpf(1.f + __builtin_amdgcn_exp2f(-1.4426950408889634f * (x))))
; template<int THRL,bool NOMAX> __device__ __forceinline__ void attn_unit(int b,int h,int qb,int t0,const bf16*Q,const bf16*__restrict__ KV,const bf16*__restrict__ GA,bf16*O,char*shm){
;     ...
;   {auto rr=__builtin_amdgcn_permlane32_swap(__float_as_uint(l_reg),__float_as_uint(l_reg),false,false);l_reg=__uint_as_float(rr[0])+__uint_as_float(rr[1]);}
;   if(hi==0)wsf[32+r32]=l_reg;asm volatile("s_waitcnt lgkmcnt(0)":::"memory");
;   float rli[16];
;   #pragma unroll
;   for(int r=0;r<16;++r)rli[r]=__builtin_amdgcn_rcpf(wsf[32+crow(r,hi)]);
;   bf16*Ow=O+(rowbase+q0+wid*QBLK)*QP+h*D; const bf16*Gw=GA+(rowbase+q0+wid*QBLK)*GP+h*D;
;   u32x4 gpre[4];
;   #pragma unroll
;   for(int i=0;i<4;++i)gpre[i]=*(const u32x4*)(Gw+(long)(i*8+(lane>>3))*GP+(lane&7)*8);
;   { float*stg=(float*)(shm+LDS_OST)+wid*2048;
;     #pragma unroll
;     for(int r=0;r<16;++r){const int orow=crow(r,hi);
;       #pragma unroll
;       for(int d0=0;d0<2;++d0)stg[orow*64+d0*32+r32]=o[d0][r]*rli[r];}
;     asm volatile("s_waitcnt lgkmcnt(0)":::"memory");
;     #pragma unroll
;     for(int i=0;i<4;++i){const int row=i*8+(lane>>3),ch=lane&7;
;       const f32x4_t a=*(const f32x4_t*)(stg+row*64+ch*8),c=*(const f32x4_t*)(stg+row*64+ch*8+4);
;       const u32x4 g=gpre[i]; u32x4 v;
;     ...
;       const float g0=__uint_as_float(g.x<<16),g1=__uint_as_float(g.x&0xffff0000u),g2=__uint_as_float(g.y<<16),g3=__uint_as_float(g.y&0xffff0000u),g4=__uint_as_float(g.z<<16),g5=__uint_as_float(g.z&0xffff0000u),g6=__uint_as_float(g.w<<16),g7=__uint_as_float(g.w&0xffff0000u);
;       v.x=cvtpk_s(a[0]*SILU_(g0),a[1]*SILU_(g1)); v.y=cvtpk_s(a[2]*SILU_(g2),a[3]*SILU_(g3));
;       v.z=cvtpk_s(c[0]*SILU_(g4),c[1]*SILU_(g5)); v.w=cvtpk_s(c[2]*SILU_(g6),c[3]*SILU_(g7));
.LBB0_470:
	s_or_b64 exec, exec, s[8:9]
	s_waitcnt lgkmcnt(0)
	v_lshl_add_u32 v2, v186, 4, s12
	ds_read_b128 v[36:39], v2 offset:49280
	ds_read_b128 v[40:43], v2 offset:49312
	s_lshl_b64 s[4:5], s[4:5], 1
	s_add_u32 s4, s84, s4
	s_addc_u32 s5, s85, s5
	s_waitcnt lgkmcnt(1)
	v_rcp_f32_e32 v52, v36
	v_rcp_f32_e32 v53, v37
	v_rcp_f32_e32 v54, v38
	v_rcp_f32_e32 v55, v39
	ds_read_b128 v[36:39], v2 offset:49344
	s_add_u32 s4, s4, s6
	v_and_b32_e32 v65, 56, v187
	s_waitcnt lgkmcnt(1)
	v_rcp_f32_e32 v56, v40
	v_rcp_f32_e32 v57, v41
	v_rcp_f32_e32 v58, v42
	v_rcp_f32_e32 v59, v43
	ds_read_b128 v[40:43], v2 offset:49376
	s_waitcnt lgkmcnt(1)
	v_rcp_f32_e32 v62, v38
	s_addc_u32 s5, s5, s7
	v_lshlrev_b32_e32 v2, 1, v65
	v_lshlrev_b32_e32 v38, 8, v184
	v_rcp_f32_e32 v60, v36
	v_rcp_f32_e32 v61, v37
	v_rcp_f32_e32 v63, v39
	v_lshl_add_u64 v[36:37], s[4:5], 0, v[2:3]
	v_and_b32_e32 v38, 0x3800, v38
	v_mov_b32_e32 v39, v3
	v_lshl_add_u64 v[36:37], v[36:37], 0, v[38:39]
	v_mov_b64_e32 v[44:45], v[206:207]
	v_mov_b64_e32 v[46:47], v[208:209]
	s_movk_i32 s4, 0x4000
	v_add_co_u32_e32 v38, vcc, s4, v36
	s_mov_b32 s4, 0x8000
	s_nop 0
	v_addc_co_u32_e32 v39, vcc, 0, v37, vcc
	v_mov_b64_e32 v[48:49], v[210:211]
	v_mov_b64_e32 v[50:51], v[212:213]
	v_add_co_u32_e32 v38, vcc, s4, v36
	s_mov_b32 s4, 0xc000
	s_nop 0
	v_addc_co_u32_e32 v39, vcc, 0, v37, vcc
	v_add_co_u32_e32 v36, vcc, s4, v36
	s_lshl_b32 s4, s11, 13
	s_add_i32 s4, s4, 0
	v_lshlrev_b32_e32 v69, 2, v185
	v_add3_u32 v69, s4, v188, v69
	v_addc_co_u32_e32 v37, vcc, 0, v37, vcc
	v_mul_f32_e32 v4, v4, v52
	v_mul_f32_e32 v20, v20, v52
	v_add_u32_e32 v52, 0xc800, v69
	s_waitcnt lgkmcnt(0)
	v_rcp_f32_e32 v64, v40
	v_rcp_f32_e32 v66, v41
	v_rcp_f32_e32 v67, v42
	v_rcp_f32_e32 v68, v43
	v_mov_b64_e32 v[40:41], v[214:215]
	v_mov_b64_e32 v[42:43], v[216:217]
	s_nop 0
	v_mov_b64_e32 v[36:37], v[218:219]
	v_mov_b64_e32 v[38:39], v[220:221]
	ds_write2_b32 v52, v4, v20 offset1:32
	v_mul_f32_e32 v4, v5, v53
	v_mul_f32_e32 v5, v21, v53
	ds_write2_b32 v52, v4, v5 offset0:64 offset1:96
	v_mul_f32_e32 v4, v6, v54
	v_mul_f32_e32 v5, v22, v54
	ds_write2_b32 v52, v4, v5 offset0:128 offset1:160
	v_mul_f32_e32 v4, v7, v55
	v_mul_f32_e32 v5, v23, v55
	ds_write2_b32 v52, v4, v5 offset0:192 offset1:224
	v_mul_f32_e32 v4, v8, v56
	v_mul_f32_e32 v5, v24, v56
	v_add_u32_e32 v6, 0xd000, v69
	ds_write2_b32 v6, v4, v5 offset1:32
	v_mul_f32_e32 v4, v9, v57
	v_mul_f32_e32 v5, v25, v57
	ds_write2_b32 v6, v4, v5 offset0:64 offset1:96
	v_mul_f32_e32 v4, v10, v58
	v_mul_f32_e32 v5, v26, v58
	ds_write2_b32 v6, v4, v5 offset0:128 offset1:160
	v_mul_f32_e32 v4, v11, v59
	v_mul_f32_e32 v5, v27, v59
	ds_write2_b32 v6, v4, v5 offset0:192 offset1:224
	v_mul_f32_e32 v4, v12, v60
	v_mul_f32_e32 v5, v28, v60
	v_add_u32_e32 v6, 0xd800, v69
	ds_write2_b32 v6, v4, v5 offset1:32
	v_mul_f32_e32 v4, v13, v61
	v_mul_f32_e32 v5, v29, v61
	ds_write2_b32 v6, v4, v5 offset0:64 offset1:96
	v_mul_f32_e32 v4, v14, v62
	v_mul_f32_e32 v5, v30, v62
	ds_write2_b32 v6, v4, v5 offset0:128 offset1:160
	v_mul_f32_e32 v4, v15, v63
	v_mul_f32_e32 v5, v31, v63
	ds_write2_b32 v6, v4, v5 offset0:192 offset1:224
	v_mul_f32_e32 v4, v16, v64
	v_mul_f32_e32 v5, v32, v64
	v_add_u32_e32 v6, 0xe000, v69
	ds_write2_b32 v6, v4, v5 offset1:32
	v_mul_f32_e32 v4, v17, v66
	v_mul_f32_e32 v5, v33, v66
	ds_write2_b32 v6, v4, v5 offset0:64 offset1:96
	v_mul_f32_e32 v4, v18, v67
	v_mul_f32_e32 v5, v34, v67
	ds_write2_b32 v6, v4, v5 offset0:128 offset1:160
	v_mul_f32_e32 v4, v19, v68
	v_mul_f32_e32 v5, v35, v68
	ds_write2_b32 v6, v4, v5 offset0:192 offset1:224
	v_lshrrev_b32_e32 v22, 3, v184
	v_lshl_add_u32 v23, v65, 2, s4
	s_waitcnt vmcnt(3)
	v_lshlrev_b32_e32 v14, 16, v44
	v_and_b32_e32 v15, 0xffff0000, v44
	v_mul_f32_e32 v6, 0xbfb8aa3b, v14
	v_exp_f32_e32 v16, v6
	v_mul_f32_e32 v6, 0xbfb8aa3b, v15
	v_exp_f32_e32 v17, v6
	s_waitcnt lgkmcnt(0)
	v_lshl_add_u64 v[4:5], s[0:1], 0, v[2:3]
	v_lshl_add_u32 v2, v22, 8, v23
	ds_read_b128 v[6:9], v2 offset:51200
	ds_read_b128 v[10:13], v2 offset:51216
	v_add_f32_e32 v2, 1.0, v16
	v_lshlrev_b32_e32 v18, 16, v45
	v_rcp_f32_e32 v16, v2
	v_add_f32_e32 v2, 1.0, v17
	v_and_b32_e32 v19, 0xffff0000, v45
	v_mul_f32_e32 v17, 0xbfb8aa3b, v18
	v_exp_f32_e32 v20, v17
	v_mul_f32_e32 v17, 0xbfb8aa3b, v19
	v_exp_f32_e32 v21, v17
	v_rcp_f32_e32 v17, v2
	v_add_f32_e32 v2, 1.0, v20
	v_rcp_f32_e32 v20, v2
	v_add_f32_e32 v2, 1.0, v21
	v_rcp_f32_e32 v21, v2
	v_pk_mul_f32 v[14:15], v[16:17], v[14:15]
	v_and_b32_e32 v17, 0xffff0000, v47
	s_waitcnt lgkmcnt(1)
	v_pk_mul_f32 v[6:7], v[14:15], v[6:7]
	v_pk_mul_f32 v[14:15], v[20:21], v[18:19]
	v_cvt_pk_bf16_f32 v6, v6, v7
	v_pk_mul_f32 v[8:9], v[14:15], v[8:9]
	v_lshlrev_b32_e32 v14, 16, v46
	v_and_b32_e32 v15, 0xffff0000, v46
	v_mul_f32_e32 v2, 0xbfb8aa3b, v14
	v_exp_f32_e32 v2, v2
	v_mul_f32_e32 v7, 0xbfb8aa3b, v15
	v_exp_f32_e32 v16, v7
	v_cvt_pk_bf16_f32 v7, v8, v9
	v_add_f32_e32 v2, 1.0, v2
	v_rcp_f32_e32 v8, v2
	v_add_f32_e32 v2, 1.0, v16
	v_lshlrev_b32_e32 v16, 16, v47
	v_mul_f32_e32 v9, 0xbfb8aa3b, v16
	v_exp_f32_e32 v18, v9
	v_mul_f32_e32 v9, 0xbfb8aa3b, v17
	v_exp_f32_e32 v19, v9
	v_rcp_f32_e32 v9, v2
	v_add_f32_e32 v2, 1.0, v18
	v_rcp_f32_e32 v18, v2
	v_add_f32_e32 v2, 1.0, v19
	v_rcp_f32_e32 v19, v2
	v_pk_mul_f32 v[8:9], v[8:9], v[14:15]
	v_lshlrev_b32_e32 v2, 11, v22
	s_waitcnt lgkmcnt(0)
	v_pk_mul_f32 v[8:9], v[8:9], v[10:11]
	v_pk_mul_f32 v[10:11], v[18:19], v[16:17]
	v_cvt_pk_bf16_f32 v8, v8, v9
	v_pk_mul_f32 v[10:11], v[10:11], v[12:13]
	s_waitcnt vmcnt(2)
; __device__ __forceinline__ unsigned cvtpk_s(float lo,float hi){f32x2_t v={lo,hi};bf16x2_t b=__builtin_convertvector(v,bf16x2_t);return __builtin_bit_cast(unsigned,b);}
;       #define SILU_(x) ((x)*__builtin_amdgcn_rcpf(1.f+__builtin_amdgcn_exp2f(-1.4426950408889634f*(x))))
; #define SILU_(x) ((x) * __builtin_amdgcn_rcpf(1.f + __builtin_amdgcn_exp2f(-1.4426950408889634f * (x))))
; template<int THRL,bool NOMAX> __device__ __forceinline__ void attn_unit(int b,int h,int qb,int t0,const bf16*Q,const bf16*__restrict__ KV,const bf16*__restrict__ GA,bf16*O,char*shm){
;     ...
;     for(int i=0;i<4;++i){const int row=i*8+(lane>>3),ch=lane&7;
;       const f32x4_t a=*(const f32x4_t*)(stg+row*64+ch*8),c=*(const f32x4_t*)(stg+row*64+ch*8+4);
;       const u32x4 g=gpre[i]; u32x4 v;
;     ...
;       const float g0=__uint_as_float(g.x<<16),g1=__uint_as_float(g.x&0xffff0000u),g2=__uint_as_float(g.y<<16),g3=__uint_as_float(g.y&0xffff0000u),g4=__uint_as_float(g.z<<16),g5=__uint_as_float(g.z&0xffff0000u),g6=__uint_as_float(g.w<<16),g7=__uint_as_float(g.w&0xffff0000u);
;       v.x=cvtpk_s(a[0]*SILU_(g0),a[1]*SILU_(g1)); v.y=cvtpk_s(a[2]*SILU_(g2),a[3]*SILU_(g3));
;       v.z=cvtpk_s(c[0]*SILU_(g4),c[1]*SILU_(g5)); v.w=cvtpk_s(c[2]*SILU_(g6),c[3]*SILU_(g7));
;     ...
;       ATTN_STORE16(Ow+(long)row*QP+ch*8,v);} }
;   asm volatile("s_waitcnt lgkmcnt(0)\n\ts_barrier":::"memory");
	v_lshlrev_b32_e32 v14, 16, v48
	v_cvt_pk_bf16_f32 v9, v10, v11
	v_lshl_add_u64 v[10:11], v[4:5], 0, v[2:3]
	global_store_dwordx4 v[10:11], v[6:9], off
	v_and_b32_e32 v15, 0xffff0000, v48
	v_lshlrev_b32_e32 v18, 16, v49
	v_mul_f32_e32 v6, 0xbfb8aa3b, v14
	v_exp_f32_e32 v16, v6
	v_mul_f32_e32 v6, 0xbfb8aa3b, v15
	v_and_b32_e32 v19, 0xffff0000, v49
	v_exp_f32_e32 v17, v6
	v_mul_f32_e32 v20, 0xbfb8aa3b, v18
	v_mul_f32_e32 v21, 0xbfb8aa3b, v19
	v_exp_f32_e32 v20, v20
	v_exp_f32_e32 v21, v21
	v_or_b32_e32 v2, 8, v22
	v_add_f32_e32 v16, 1.0, v16
	v_add_f32_e32 v17, 1.0, v17
	v_lshl_add_u32 v10, v2, 8, v23
	v_rcp_f32_e32 v16, v16
	v_rcp_f32_e32 v17, v17
	v_add_f32_e32 v20, 1.0, v20
	v_add_f32_e32 v21, 1.0, v21
	ds_read_b128 v[6:9], v10 offset:51200
	ds_read_b128 v[10:13], v10 offset:51216
	v_rcp_f32_e32 v20, v20
	v_rcp_f32_e32 v21, v21
	v_pk_mul_f32 v[14:15], v[16:17], v[14:15]
	v_lshlrev_b32_e32 v2, 11, v2
	s_waitcnt lgkmcnt(1)
	v_pk_mul_f32 v[6:7], v[14:15], v[6:7]
	v_pk_mul_f32 v[14:15], v[20:21], v[18:19]
	v_cvt_pk_bf16_f32 v6, v6, v7
	v_pk_mul_f32 v[8:9], v[14:15], v[8:9]
	v_lshlrev_b32_e32 v14, 16, v50
	v_and_b32_e32 v15, 0xffff0000, v50
	v_mul_f32_e32 v7, 0xbfb8aa3b, v14
	v_exp_f32_e32 v16, v7
	v_mul_f32_e32 v7, 0xbfb8aa3b, v15
	v_exp_f32_e32 v17, v7
	v_cvt_pk_bf16_f32 v7, v8, v9
	v_add_f32_e32 v8, 1.0, v16
	v_lshlrev_b32_e32 v16, 16, v51
	v_add_f32_e32 v9, 1.0, v17
	v_and_b32_e32 v17, 0xffff0000, v51
	v_mul_f32_e32 v18, 0xbfb8aa3b, v16
	v_mul_f32_e32 v19, 0xbfb8aa3b, v17
	v_exp_f32_e32 v18, v18
	v_exp_f32_e32 v19, v19
	v_rcp_f32_e32 v8, v8
	v_rcp_f32_e32 v9, v9
	v_add_f32_e32 v18, 1.0, v18
	v_add_f32_e32 v19, 1.0, v19
	v_rcp_f32_e32 v18, v18
	v_rcp_f32_e32 v19, v19
	v_pk_mul_f32 v[8:9], v[8:9], v[14:15]
	s_waitcnt vmcnt(2)
	v_lshlrev_b32_e32 v14, 16, v40
	s_waitcnt lgkmcnt(0)
	v_pk_mul_f32 v[8:9], v[8:9], v[10:11]
	v_pk_mul_f32 v[10:11], v[18:19], v[16:17]
	v_cvt_pk_bf16_f32 v8, v8, v9
	v_pk_mul_f32 v[10:11], v[10:11], v[12:13]
	v_and_b32_e32 v15, 0xffff0000, v40
	v_cvt_pk_bf16_f32 v9, v10, v11
	v_lshl_add_u64 v[10:11], v[4:5], 0, v[2:3]
	global_store_dwordx4 v[10:11], v[6:9], off
	v_lshlrev_b32_e32 v18, 16, v41
	v_and_b32_e32 v19, 0xffff0000, v41
	v_mul_f32_e32 v6, 0xbfb8aa3b, v14
	v_exp_f32_e32 v16, v6
	v_mul_f32_e32 v6, 0xbfb8aa3b, v15
	v_exp_f32_e32 v17, v6
	v_mul_f32_e32 v20, 0xbfb8aa3b, v18
	v_mul_f32_e32 v21, 0xbfb8aa3b, v19
	v_exp_f32_e32 v20, v20
	v_exp_f32_e32 v21, v21
	v_or_b32_e32 v2, 16, v22
	v_add_f32_e32 v16, 1.0, v16
	v_add_f32_e32 v17, 1.0, v17
	v_lshl_add_u32 v10, v2, 8, v23
	v_rcp_f32_e32 v16, v16
	v_rcp_f32_e32 v17, v17
	v_add_f32_e32 v20, 1.0, v20
	v_add_f32_e32 v21, 1.0, v21
	ds_read_b128 v[6:9], v10 offset:51200
	ds_read_b128 v[10:13], v10 offset:51216
	v_rcp_f32_e32 v20, v20
	v_rcp_f32_e32 v21, v21
	v_pk_mul_f32 v[14:15], v[16:17], v[14:15]
	v_lshlrev_b32_e32 v2, 11, v2
	s_waitcnt lgkmcnt(1)
	v_pk_mul_f32 v[6:7], v[14:15], v[6:7]
	v_pk_mul_f32 v[14:15], v[20:21], v[18:19]
	v_cvt_pk_bf16_f32 v6, v6, v7
	v_pk_mul_f32 v[8:9], v[14:15], v[8:9]
	v_lshlrev_b32_e32 v14, 16, v42
	v_and_b32_e32 v15, 0xffff0000, v42
	v_mul_f32_e32 v7, 0xbfb8aa3b, v14
	v_exp_f32_e32 v16, v7
	v_mul_f32_e32 v7, 0xbfb8aa3b, v15
	v_exp_f32_e32 v17, v7
	v_cvt_pk_bf16_f32 v7, v8, v9
	v_add_f32_e32 v8, 1.0, v16
	v_lshlrev_b32_e32 v16, 16, v43
	v_add_f32_e32 v9, 1.0, v17
	v_and_b32_e32 v17, 0xffff0000, v43
	v_mul_f32_e32 v18, 0xbfb8aa3b, v16
	v_mul_f32_e32 v19, 0xbfb8aa3b, v17
	v_exp_f32_e32 v18, v18
	v_exp_f32_e32 v19, v19
	v_rcp_f32_e32 v8, v8
	v_rcp_f32_e32 v9, v9
	v_add_f32_e32 v18, 1.0, v18
	v_add_f32_e32 v19, 1.0, v19
	v_rcp_f32_e32 v18, v18
	v_rcp_f32_e32 v19, v19
	v_pk_mul_f32 v[8:9], v[8:9], v[14:15]
	s_waitcnt vmcnt(2)
	v_lshlrev_b32_e32 v14, 16, v36
	s_waitcnt lgkmcnt(0)
	v_pk_mul_f32 v[8:9], v[8:9], v[10:11]
	v_pk_mul_f32 v[10:11], v[18:19], v[16:17]
	v_cvt_pk_bf16_f32 v8, v8, v9
	v_pk_mul_f32 v[10:11], v[10:11], v[12:13]
	v_and_b32_e32 v15, 0xffff0000, v36
	v_cvt_pk_bf16_f32 v9, v10, v11
	v_lshl_add_u64 v[10:11], v[4:5], 0, v[2:3]
	global_store_dwordx4 v[10:11], v[6:9], off
	v_lshlrev_b32_e32 v18, 16, v37
	v_and_b32_e32 v19, 0xffff0000, v37
	v_mul_f32_e32 v6, 0xbfb8aa3b, v14
	v_exp_f32_e32 v16, v6
	v_mul_f32_e32 v6, 0xbfb8aa3b, v15
	v_exp_f32_e32 v17, v6
	v_mul_f32_e32 v20, 0xbfb8aa3b, v18
	v_mul_f32_e32 v21, 0xbfb8aa3b, v19
	v_exp_f32_e32 v20, v20
	v_exp_f32_e32 v21, v21
	v_or_b32_e32 v2, 24, v22
	v_add_f32_e32 v16, 1.0, v16
	v_add_f32_e32 v17, 1.0, v17
	v_lshl_add_u32 v10, v2, 8, v23
	v_rcp_f32_e32 v16, v16
	v_rcp_f32_e32 v17, v17
	v_add_f32_e32 v20, 1.0, v20
	v_add_f32_e32 v21, 1.0, v21
	ds_read_b128 v[6:9], v10 offset:51200
	ds_read_b128 v[10:13], v10 offset:51216
	v_rcp_f32_e32 v20, v20
	v_rcp_f32_e32 v21, v21
	v_pk_mul_f32 v[14:15], v[16:17], v[14:15]
	v_lshlrev_b32_e32 v2, 11, v2
	s_waitcnt lgkmcnt(1)
	v_pk_mul_f32 v[6:7], v[14:15], v[6:7]
	v_pk_mul_f32 v[14:15], v[20:21], v[18:19]
	v_cvt_pk_bf16_f32 v6, v6, v7
	v_pk_mul_f32 v[8:9], v[14:15], v[8:9]
	v_lshlrev_b32_e32 v14, 16, v38
	v_and_b32_e32 v15, 0xffff0000, v38
	v_mul_f32_e32 v7, 0xbfb8aa3b, v14
	v_exp_f32_e32 v16, v7
	v_mul_f32_e32 v7, 0xbfb8aa3b, v15
	v_exp_f32_e32 v17, v7
	v_cvt_pk_bf16_f32 v7, v8, v9
	v_add_f32_e32 v8, 1.0, v16
	v_lshlrev_b32_e32 v16, 16, v39
	v_add_f32_e32 v9, 1.0, v17
	v_and_b32_e32 v17, 0xffff0000, v39
	v_mul_f32_e32 v18, 0xbfb8aa3b, v16
	v_mul_f32_e32 v19, 0xbfb8aa3b, v17
	v_exp_f32_e32 v18, v18
	v_exp_f32_e32 v19, v19
	v_rcp_f32_e32 v8, v8
	v_rcp_f32_e32 v9, v9
	v_add_f32_e32 v18, 1.0, v18
	v_add_f32_e32 v19, 1.0, v19
	v_rcp_f32_e32 v18, v18
	v_rcp_f32_e32 v19, v19
	v_pk_mul_f32 v[8:9], v[8:9], v[14:15]
	v_lshl_add_u64 v[4:5], v[4:5], 0, v[2:3]
	s_waitcnt lgkmcnt(0)
	v_pk_mul_f32 v[8:9], v[8:9], v[10:11]
	v_pk_mul_f32 v[10:11], v[18:19], v[16:17]
	v_cvt_pk_bf16_f32 v8, v8, v9
	v_pk_mul_f32 v[10:11], v[10:11], v[12:13]
	s_add_i32 s10, s10, 1
	v_cvt_pk_bf16_f32 v9, v10, v11
	global_store_dwordx4 v[4:5], v[6:9], off
	s_waitcnt lgkmcnt(0)
	s_barrier
	s_mov_b64 s[4:5], 0

;   #define RESC() do{ if(resc){ asm volatile("s_waitcnt lgkmcnt(0)":::"memory"); \
;       _Pragma("unroll") for(int d_=0;d_<2;++d_) _Pragma("unroll") for(int r=0;r<16;++r)o[d_][r]*=wsf[crow(r,hi)]; } }while(0)
;   #define ROT() do{sl_prev=sl_cur;sl_cur=sl_next;sl_next=(sl_next==(NSLOT-1)*SLOTB)?0:sl_next+SLOTB;}while(0)
;   #define WAIT_STEADY() WAIT_BAR(3)
;   #define WAIT_STEADY() WAIT_BAR(2)
; template<int THRL,bool NOMAX> __device__ __forceinline__ void attn_unit(int b,int h,int qb,int t0,const bf16*Q,const bf16*__restrict__ KV,const bf16*__restrict__ GA,bf16*O,char*shm){
;     ...
;   for(;t+5<NT;t+=2){
;     STEP(pB0,pB1,pA0,pA1,t,true,true,true);     WAIT_STEADY(); RESC(); ROT();
.LBB0_479:
	v_add_u32_e32 v179, s16, v2
	ds_read_b64_tr_b16 v[198:199], v179 offset:24576
	ds_read_b64_tr_b16 v[200:201], v179 offset:25088
	v_add_f32_e32 v88, v68, v69
	v_add_f32_e32 v88, v70, v88
	v_add_f32_e32 v88, v71, v88
	v_add_f32_e32 v88, v72, v88
	v_add_f32_e32 v88, v73, v88
	v_cvt_pk_bf16_f32 v160, v68, v69
	v_cvt_pk_bf16_f32 v161, v70, v71
	v_mfma_f32_32x32x16_bf16 v[100:115], v[84:87], v[152:155], v[36:51]
	ds_read_b64_tr_b16 v[202:203], v179 offset:28672
	ds_read_b64_tr_b16 v[204:205], v179 offset:29184
	v_add_f32_e32 v68, v74, v88
	v_mfma_f32_32x32x16_bf16 v[84:99], v[168:171], v[152:155], v[36:51]
	v_add_f32_e32 v68, v75, v68
	v_add_f32_e32 v68, v76, v68
	v_add_f32_e32 v140, v77, v68
	v_cvt_pk_bf16_f32 v162, v72, v73
	v_cvt_pk_bf16_f32 v163, v74, v75
	ds_read_b64_tr_b16 v[68:69], v179 offset:25600
	ds_read_b64_tr_b16 v[70:71], v179 offset:26112
	v_add_f32_e32 v72, v78, v140
	v_add_f32_e32 v72, v79, v72
	v_add_f32_e32 v72, v80, v72
	v_add_f32_e32 v140, v81, v72
	v_cvt_pk_bf16_f32 v156, v76, v77
	v_cvt_pk_bf16_f32 v157, v78, v79
	v_mfma_f32_32x32x16_bf16 v[100:115], v[172:175], v[144:147], v[100:115]
	ds_read_b64_tr_b16 v[72:73], v179 offset:29696
	ds_read_b64_tr_b16 v[74:75], v179 offset:30208
	v_mfma_f32_32x32x16_bf16 v[84:99], v[164:167], v[144:147], v[84:99]
	v_add_f32_e32 v76, v82, v140
	v_add_f32_e32 v76, v83, v76
	v_add_f32_e32 v76, v52, v76
	v_add_f32_e32 v140, v53, v76
	v_cvt_pk_bf16_f32 v158, v80, v81
	v_cvt_pk_bf16_f32 v159, v82, v83
	ds_read_b64_tr_b16 v[76:77], v179 offset:26624
	ds_read_b64_tr_b16 v[78:79], v179 offset:27136
	v_add_f32_e32 v80, v54, v140
	v_add_f32_e32 v80, v55, v80
	v_add_f32_e32 v80, v56, v80
	v_add_f32_e32 v80, v57, v80
	v_cvt_pk_bf16_f32 v148, v52, v53
	v_cvt_pk_bf16_f32 v149, v54, v55
	v_mfma_f32_32x32x16_bf16 v[100:115], v[128:131], v[136:139], v[100:115]
	ds_read_b64_tr_b16 v[52:53], v179 offset:30720
	ds_read_b64_tr_b16 v[54:55], v179 offset:31232
	v_mfma_f32_32x32x16_bf16 v[84:99], v[124:127], v[136:139], v[84:99]
	v_add_f32_e32 v80, v58, v80
	v_add_f32_e32 v80, v59, v80
	v_add_f32_e32 v80, v60, v80
	v_add_f32_e32 v80, v61, v80
	v_cvt_pk_bf16_f32 v150, v56, v57
	v_cvt_pk_bf16_f32 v151, v58, v59
	ds_read_b64_tr_b16 v[56:57], v179 offset:27648
	ds_read_b64_tr_b16 v[58:59], v179 offset:28160
	v_add_f32_e32 v80, v62, v80
	v_add_f32_e32 v80, v63, v80
	v_add_f32_e32 v80, v64, v80
	v_add_f32_e32 v80, v65, v80
	v_cvt_pk_bf16_f32 v140, v60, v61
	v_cvt_pk_bf16_f32 v141, v62, v63
	v_mfma_f32_32x32x16_bf16 v[100:115], v[120:123], v[132:135], v[100:115]
	ds_read_b64_tr_b16 v[60:61], v179 offset:31744
	ds_read_b64_tr_b16 v[62:63], v179 offset:32256
	v_mfma_f32_32x32x16_bf16 v[84:99], v[116:119], v[132:135], v[84:99]
	v_add_f32_e32 v80, v66, v80
	v_add_f32_e32 v80, v67, v80
	v_add_f32_e32 v179, 0, v80
	v_cvt_pk_bf16_f32 v142, v64, v65
	v_cvt_pk_bf16_f32 v143, v66, v67
	s_add_i32 s16, s21, 0x4000
	s_and_b32 s16, s16, 0xfc000
	s_lshl_b32 s16, s16, 1
	v_lshl_add_u64 v[218:219], v[182:183], 0, s[16:17]
	s_add_i32 m0, s22, s9
	s_nop 0
	global_load_lds_dwordx4 v[218:219], off
	s_waitcnt lgkmcnt(4)
	v_mfma_f32_32x32x16_bf16 v[4:19], v[160:163], v[198:201], v[4:19]
	v_exp_f32_e32 v100, v100
	v_exp_f32_e32 v101, v101
	v_exp_f32_e32 v102, v102
	v_exp_f32_e32 v103, v103
	v_mfma_f32_32x32x16_bf16 v[20:35], v[160:163], v[202:205], v[20:35]
	v_exp_f32_e32 v104, v104
	v_exp_f32_e32 v105, v105
	v_exp_f32_e32 v106, v106
	v_exp_f32_e32 v107, v107
	v_add_u32_e32 v80, s15, v189
	ds_read_b128 v[64:67], v80
	ds_read_b128 v[120:123], v80 offset:512
	v_mfma_f32_32x32x16_bf16 v[4:19], v[156:159], v[68:71], v[4:19]
	v_exp_f32_e32 v108, v108
	v_exp_f32_e32 v109, v109
	v_exp_f32_e32 v110, v110
	v_exp_f32_e32 v111, v111
	ds_read_b128 v[124:127], v80 offset:2048
	ds_read_b128 v[128:131], v80 offset:2560
	v_mfma_f32_32x32x16_bf16 v[20:35], v[156:159], v[72:75], v[20:35]
	v_exp_f32_e32 v112, v112
	v_exp_f32_e32 v113, v113
	v_exp_f32_e32 v114, v114
	v_exp_f32_e32 v115, v115
	ds_read_b128 v[164:167], v80 offset:4096
	ds_read_b128 v[168:171], v80 offset:4608
	v_mfma_f32_32x32x16_bf16 v[4:19], v[148:151], v[76:79], v[4:19]
	v_exp_f32_e32 v84, v84
	v_exp_f32_e32 v85, v85
	v_exp_f32_e32 v86, v86
	v_exp_f32_e32 v87, v87
	ds_read_b128 v[172:175], v80 offset:6144
	ds_read_b128 v[116:119], v80 offset:6656
	v_mfma_f32_32x32x16_bf16 v[20:35], v[148:151], v[52:55], v[20:35]
	v_exp_f32_e32 v88, v88
	v_exp_f32_e32 v89, v89
	v_exp_f32_e32 v90, v90
	v_exp_f32_e32 v91, v91
	s_waitcnt lgkmcnt(8)
	v_mfma_f32_32x32x16_bf16 v[4:19], v[140:143], v[56:59], v[4:19]
	v_exp_f32_e32 v92, v92
	v_exp_f32_e32 v93, v93
	v_exp_f32_e32 v94, v94
	v_exp_f32_e32 v95, v95
	v_mfma_f32_32x32x16_bf16 v[20:35], v[140:143], v[60:63], v[20:35]
	v_exp_f32_e32 v96, v96
	v_exp_f32_e32 v97, v97
	v_exp_f32_e32 v98, v98
	v_exp_f32_e32 v99, v99
	s_add_i32 s16, s20, 0xffff4000
	s_and_b32 s16, s16, 0xfc000
	s_lshl_b32 s16, s16, 1
	v_lshl_add_u64 v[218:219], v[180:181], 0, s[16:17]
	s_add_i32 m0, s15, s8
	s_nop 0
	global_load_lds_dwordx4 v[218:219], off
	s_waitcnt vmcnt(2) lgkmcnt(0)
	s_barrier
;   #define RESC() do{ if(resc){ asm volatile("s_waitcnt lgkmcnt(0)":::"memory"); \
;       _Pragma("unroll") for(int d_=0;d_<2;++d_) _Pragma("unroll") for(int r=0;r<16;++r)o[d_][r]*=wsf[crow(r,hi)]; } }while(0)
;   #define ROT() do{sl_prev=sl_cur;sl_cur=sl_next;sl_next=(sl_next==(NSLOT-1)*SLOTB)?0:sl_next+SLOTB;}while(0)
;   #define WAIT_STEADY() WAIT_BAR(3)
;   #define WAIT_STEADY() WAIT_BAR(2)
; template<int THRL,bool NOMAX> __device__ __forceinline__ void attn_unit(int b,int h,int qb,int t0,const bf16*Q,const bf16*__restrict__ KV,const bf16*__restrict__ GA,bf16*O,char*shm){
;     ...
;   for(;t+5<NT;t+=2){
;     STEP(pB0,pB1,pA0,pA1,t,true,true,true);     WAIT_STEADY(); RESC(); ROT();
;     STEP(pA0,pA1,pB0,pB1,t+1,true,true,true);   WAIT_STEADY(); RESC(); ROT();
;   }
	s_add_i32 s16, s15, 0x2000
	s_cmpk_lg_i32 s15, 0x4000
	s_cselect_b32 s23, s16, 0
	v_add_u32_e32 v190, s22, v2
	ds_read_b64_tr_b16 v[198:199], v190 offset:24576
	ds_read_b64_tr_b16 v[200:201], v190 offset:25088
	v_mfma_f32_32x32x16_bf16 v[68:83], v[64:67], v[152:155], v[36:51]
	v_add_f32_e32 v52, v100, v101
	v_add_f32_e32 v52, v102, v52
	v_add_f32_e32 v52, v103, v52
	v_add_f32_e32 v52, v104, v52
	v_add_f32_e32 v52, v105, v52
	v_cvt_pk_bf16_f32 v160, v100, v101
	v_cvt_pk_bf16_f32 v161, v102, v103
	ds_read_b64_tr_b16 v[202:203], v190 offset:28672
	ds_read_b64_tr_b16 v[204:205], v190 offset:29184
	v_add_f32_e32 v52, v106, v52
	v_add_f32_e32 v52, v107, v52
	v_add_f32_e32 v52, v108, v52
	v_add_f32_e32 v140, v109, v52
	v_mfma_f32_32x32x16_bf16 v[52:67], v[120:123], v[152:155], v[36:51]
	v_cvt_pk_bf16_f32 v162, v104, v105
	v_cvt_pk_bf16_f32 v163, v106, v107
	ds_read_b64_tr_b16 v[100:101], v190 offset:25600
	ds_read_b64_tr_b16 v[102:103], v190 offset:26112
	v_mfma_f32_32x32x16_bf16 v[68:83], v[124:127], v[144:147], v[68:83]
	v_add_f32_e32 v104, v110, v140
	v_add_f32_e32 v104, v111, v104
	v_add_f32_e32 v104, v112, v104
	v_add_f32_e32 v120, v113, v104
	v_cvt_pk_bf16_f32 v156, v108, v109
	v_cvt_pk_bf16_f32 v157, v110, v111
	ds_read_b64_tr_b16 v[104:105], v190 offset:29696
	ds_read_b64_tr_b16 v[106:107], v190 offset:30208
	v_mfma_f32_32x32x16_bf16 v[52:67], v[128:131], v[144:147], v[52:67]
	v_add_f32_e32 v108, v114, v120
	v_add_f32_e32 v108, v115, v108
	v_add_f32_e32 v108, v84, v108
	v_add_f32_e32 v120, v85, v108
	v_cvt_pk_bf16_f32 v158, v112, v113
	v_cvt_pk_bf16_f32 v159, v114, v115
	ds_read_b64_tr_b16 v[108:109], v190 offset:26624
	ds_read_b64_tr_b16 v[110:111], v190 offset:27136
	v_mfma_f32_32x32x16_bf16 v[68:83], v[164:167], v[136:139], v[68:83]
	v_add_f32_e32 v112, v86, v120
	v_add_f32_e32 v112, v87, v112
	v_add_f32_e32 v112, v88, v112
	v_add_f32_e32 v120, v89, v112
	v_cvt_pk_bf16_f32 v148, v84, v85
	v_cvt_pk_bf16_f32 v149, v86, v87
	ds_read_b64_tr_b16 v[112:113], v190 offset:30720
	ds_read_b64_tr_b16 v[114:115], v190 offset:31232
	v_mfma_f32_32x32x16_bf16 v[52:67], v[168:171], v[136:139], v[52:67]
	v_add_f32_e32 v84, v90, v120
	v_add_f32_e32 v84, v91, v84
	v_add_f32_e32 v84, v92, v84
	v_add_f32_e32 v84, v93, v84
	v_cvt_pk_bf16_f32 v150, v88, v89
	v_cvt_pk_bf16_f32 v151, v90, v91
	ds_read_b64_tr_b16 v[88:89], v190 offset:27648
	ds_read_b64_tr_b16 v[90:91], v190 offset:28160
	v_mfma_f32_32x32x16_bf16 v[68:83], v[172:175], v[132:135], v[68:83]
	v_add_f32_e32 v84, v94, v84
	v_add_f32_e32 v84, v95, v84
	v_add_f32_e32 v84, v96, v84
	v_add_f32_e32 v84, v97, v84
	v_cvt_pk_bf16_f32 v140, v92, v93
	v_cvt_pk_bf16_f32 v141, v94, v95
	ds_read_b64_tr_b16 v[92:93], v190 offset:31744
	ds_read_b64_tr_b16 v[94:95], v190 offset:32256
	v_mfma_f32_32x32x16_bf16 v[52:67], v[116:119], v[132:135], v[52:67]
	v_add_f32_e32 v84, v98, v84
	v_add_f32_e32 v84, v99, v84
	v_add_f32_e32 v190, 0, v84
	v_cvt_pk_bf16_f32 v142, v96, v97
	v_cvt_pk_bf16_f32 v143, v98, v99
	s_and_b32 s16, s20, 0xfc000
	s_lshl_b32 s16, s16, 1
	v_lshl_add_u64 v[218:219], v[182:183], 0, s[16:17]
	s_add_i32 m0, s15, s9
	s_nop 0
	global_load_lds_dwordx4 v[218:219], off
	s_waitcnt lgkmcnt(4)
	v_mfma_f32_32x32x16_bf16 v[4:19], v[160:163], v[198:201], v[4:19]
	v_exp_f32_e32 v68, v68
	v_exp_f32_e32 v69, v69
	v_exp_f32_e32 v70, v70
	v_exp_f32_e32 v71, v71
	v_mfma_f32_32x32x16_bf16 v[20:35], v[160:163], v[202:205], v[20:35]
	v_exp_f32_e32 v72, v72
	v_exp_f32_e32 v73, v73
	v_exp_f32_e32 v74, v74
	v_exp_f32_e32 v75, v75
	v_add_u32_e32 v96, s23, v189
	ds_read_b128 v[84:87], v96
	ds_read_b128 v[168:171], v96 offset:512
	v_mfma_f32_32x32x16_bf16 v[4:19], v[156:159], v[100:103], v[4:19]
	v_exp_f32_e32 v76, v76
	v_exp_f32_e32 v77, v77
	v_exp_f32_e32 v78, v78
	v_exp_f32_e32 v79, v79
	ds_read_b128 v[172:175], v96 offset:2048
	ds_read_b128 v[164:167], v96 offset:2560
	v_mfma_f32_32x32x16_bf16 v[20:35], v[156:159], v[104:107], v[20:35]
	v_exp_f32_e32 v80, v80
	v_exp_f32_e32 v81, v81
	v_exp_f32_e32 v82, v82
	v_exp_f32_e32 v83, v83
	ds_read_b128 v[128:131], v96 offset:4096
	ds_read_b128 v[124:127], v96 offset:4608
	v_mfma_f32_32x32x16_bf16 v[4:19], v[148:151], v[108:111], v[4:19]
	v_exp_f32_e32 v52, v52
	v_exp_f32_e32 v53, v53
	v_exp_f32_e32 v54, v54
	v_exp_f32_e32 v55, v55
	ds_read_b128 v[120:123], v96 offset:6144
	ds_read_b128 v[116:119], v96 offset:6656
	v_mfma_f32_32x32x16_bf16 v[20:35], v[148:151], v[112:115], v[20:35]
	v_exp_f32_e32 v56, v56
	v_exp_f32_e32 v57, v57
	v_exp_f32_e32 v58, v58
	v_exp_f32_e32 v59, v59
	s_waitcnt lgkmcnt(8)
	v_mfma_f32_32x32x16_bf16 v[4:19], v[140:143], v[88:91], v[4:19]
	v_exp_f32_e32 v60, v60
	v_exp_f32_e32 v61, v61
	v_exp_f32_e32 v62, v62
	v_exp_f32_e32 v63, v63
	v_mfma_f32_32x32x16_bf16 v[20:35], v[140:143], v[92:95], v[20:35]
	v_exp_f32_e32 v64, v64
	v_exp_f32_e32 v65, v65
	v_exp_f32_e32 v66, v66
	v_exp_f32_e32 v67, v67
	s_add_i32 s26, s23, 0x2000
	s_and_b32 s16, s21, 0xfc000
	s_lshl_b32 s16, s16, 1
	v_lshl_add_u64 v[218:219], v[180:181], 0, s[16:17]
	s_add_i32 m0, s23, s8
	s_nop 0
	global_load_lds_dwordx4 v[218:219], off
	s_waitcnt vmcnt(2) lgkmcnt(0)
	s_barrier
	s_cmpk_lg_i32 s23, 0x4000
	v_add_f32_e32 v88, v191, v179
	s_mov_b32 s16, s15
	s_cselect_b32 s15, s26, 0
	s_add_i32 s14, s14, 2
	s_add_i32 s21, s21, 0x8000
	s_add_i32 s20, s20, 0x8000
	s_mov_b32 s22, s23
	v_add_f32_e32 v191, v88, v190
	s_cmp_gt_u32 s14, 56
	s_cbranch_scc0 .LBB0_479
;   #define RESC() do{ if(resc){ asm volatile("s_waitcnt lgkmcnt(0)":::"memory"); \
;       _Pragma("unroll") for(int d_=0;d_<2;++d_) _Pragma("unroll") for(int r=0;r<16;++r)o[d_][r]*=wsf[crow(r,hi)]; } }while(0)
;   #define ROT() do{sl_prev=sl_cur;sl_cur=sl_next;sl_next=(sl_next==(NSLOT-1)*SLOTB)?0:sl_next+SLOTB;}while(0)
;   #define ENDW(tt) do{ if((tt)+3<NT){WAIT_BAR(2);} else if((tt)+2<NT){WAIT_BAR(1);} else {WAIT_BAR(0);} }while(0)
; template<int THRL,bool NOMAX> __device__ __forceinline__ void attn_unit(int b,int h,int qb,int t0,const bf16*Q,const bf16*__restrict__ KV,const bf16*__restrict__ GA,bf16*O,char*shm){
;     ...
;   for(;t+1<NT;t+=2){
;     STEP(pB0,pB1,pA0,pA1,t,(t+3<NT),(t+1<NT),(t+1<NT));       ENDW(t);   RESC(); ROT();
	s_and_b32 s12, s12, 0x3fffffc0
	s_cmp_lg_u32 0, -1
	s_cselect_b32 s14, 0, 0
	s_add_i32 s15, s14, 0x6000
	s_lshl_b32 s12, s12, 2
	v_add_u32_e32 v88, s15, v177
	s_add_i32 s12, s12, 0
	v_add3_u32 v190, v88, v176, v178
	ds_read_b64_tr_b16 v[198:199], v2 offset:32768
	ds_read_b64_tr_b16 v[200:201], v2 offset:33280
	v_add_f32_e32 v88, v68, v69
	v_add_f32_e32 v88, v70, v88
	v_add_f32_e32 v88, v71, v88
	v_add_f32_e32 v88, v72, v88
	v_add_f32_e32 v88, v73, v88
	v_cvt_pk_bf16_f32 v160, v68, v69
	v_cvt_pk_bf16_f32 v161, v70, v71
	s_waitcnt lgkmcnt(9)
	v_mfma_f32_32x32x16_bf16 v[100:115], v[84:87], v[152:155], v[36:51]
	ds_read_b64_tr_b16 v[176:177], v2 offset:36864
	ds_read_b64_tr_b16 v[178:179], v2 offset:37376
	v_add_f32_e32 v68, v74, v88
	v_add_f32_e32 v68, v75, v68
	v_add_f32_e32 v68, v76, v68
	v_add_f32_e32 v140, v77, v68
	v_cvt_pk_bf16_f32 v162, v72, v73
	v_cvt_pk_bf16_f32 v163, v74, v75
	s_waitcnt lgkmcnt(10)
	v_mfma_f32_32x32x16_bf16 v[84:99], v[168:171], v[152:155], v[36:51]
	ds_read_b64_tr_b16 v[68:69], v2 offset:33792
	ds_read_b64_tr_b16 v[70:71], v2 offset:34304
	v_add_f32_e32 v72, v78, v140
	v_add_f32_e32 v72, v79, v72
	v_add_f32_e32 v72, v80, v72
	v_add_f32_e32 v140, v81, v72
	v_cvt_pk_bf16_f32 v156, v76, v77
	v_cvt_pk_bf16_f32 v157, v78, v79
	s_waitcnt lgkmcnt(11)
	v_mfma_f32_32x32x16_bf16 v[100:115], v[172:175], v[144:147], v[100:115]
	ds_read_b64_tr_b16 v[72:73], v2 offset:37888
	ds_read_b64_tr_b16 v[74:75], v2 offset:38400
	v_add_f32_e32 v76, v82, v140
	v_add_f32_e32 v76, v83, v76
	v_add_f32_e32 v76, v52, v76
	v_add_f32_e32 v140, v53, v76
	v_cvt_pk_bf16_f32 v158, v80, v81
	v_cvt_pk_bf16_f32 v159, v82, v83
	s_waitcnt lgkmcnt(12)
	v_mfma_f32_32x32x16_bf16 v[84:99], v[164:167], v[144:147], v[84:99]
	ds_read_b64_tr_b16 v[76:77], v2 offset:34816
	ds_read_b64_tr_b16 v[78:79], v2 offset:35328
	v_add_f32_e32 v80, v54, v140
	v_add_f32_e32 v80, v55, v80
	v_add_f32_e32 v80, v56, v80
	v_add_f32_e32 v80, v57, v80
	v_cvt_pk_bf16_f32 v148, v52, v53
	v_cvt_pk_bf16_f32 v149, v54, v55
	s_waitcnt lgkmcnt(13)
	v_mfma_f32_32x32x16_bf16 v[100:115], v[128:131], v[136:139], v[100:115]
	ds_read_b64_tr_b16 v[52:53], v2 offset:38912
	ds_read_b64_tr_b16 v[54:55], v2 offset:39424
	v_add_f32_e32 v80, v58, v80
	v_add_f32_e32 v80, v59, v80
	v_add_f32_e32 v80, v60, v80
	v_add_f32_e32 v80, v61, v80
	v_cvt_pk_bf16_f32 v150, v56, v57
	v_cvt_pk_bf16_f32 v151, v58, v59
	s_waitcnt lgkmcnt(14)
	v_mfma_f32_32x32x16_bf16 v[84:99], v[124:127], v[136:139], v[84:99]
	ds_read_b64_tr_b16 v[56:57], v2 offset:35840
	ds_read_b64_tr_b16 v[58:59], v2 offset:36352
	v_add_f32_e32 v80, v62, v80
	v_add_f32_e32 v80, v63, v80
	v_add_f32_e32 v80, v64, v80
	v_add_f32_e32 v80, v65, v80
	v_cvt_pk_bf16_f32 v140, v60, v61
	v_cvt_pk_bf16_f32 v141, v62, v63
	s_waitcnt lgkmcnt(14)
	v_mfma_f32_32x32x16_bf16 v[100:115], v[120:123], v[132:135], v[100:115]
	ds_read_b64_tr_b16 v[60:61], v2 offset:39936
	ds_read_b64_tr_b16 v[62:63], v2 offset:40448
	v_add_f32_e32 v80, v66, v80
	v_add_f32_e32 v80, v67, v80
	v_add_f32_e32 v80, 0, v80
	v_cvt_pk_bf16_f32 v142, v64, v65
	v_cvt_pk_bf16_f32 v143, v66, v67
	v_mfma_f32_32x32x16_bf16 v[84:99], v[116:119], v[132:135], v[84:99]
	v_readlane_b32 s20, v254, 56
	v_readlane_b32 s21, v254, 57
	s_mov_b32 s21, s17
	s_add_i32 s13, s14, s13
	v_lshl_add_u64 v[64:65], v[182:183], 0, s[20:21]
	s_add_i32 s14, s13, 0x4000
	s_mov_b32 s15, m0
	s_mov_b32 m0, s14
	s_nop 0
	global_load_lds_dwordx4 v[64:65], off
	s_mov_b32 m0, s15
	v_add_f32_e32 v191, v191, v80
	v_readlane_b32 s14, v254, 58
	v_readlane_b32 s15, v254, 59
	s_mov_b32 s15, s17
	s_mov_b32 s16, s14
	v_lshl_add_u64 v[64:65], v[180:181], 0, s[14:15]
	s_mov_b32 s14, m0
	s_mov_b32 m0, s8
	s_nop 0
	global_load_lds_dwordx4 v[64:65], off
	s_mov_b32 m0, s14
	v_writelane_b32 v254, s16, 58
	s_nop 1
	v_writelane_b32 v254, s17, 59
	s_waitcnt lgkmcnt(14)
	v_mfma_f32_32x32x16_bf16 v[4:19], v[160:163], v[198:201], v[4:19]
	v_exp_f32_e32 v100, v100
	v_exp_f32_e32 v101, v101
	v_exp_f32_e32 v102, v102
	v_exp_f32_e32 v103, v103
	s_waitcnt lgkmcnt(12)
	v_mfma_f32_32x32x16_bf16 v[20:35], v[160:163], v[176:179], v[20:35]
	v_exp_f32_e32 v104, v104
	v_exp_f32_e32 v105, v105
	v_exp_f32_e32 v106, v106
	v_exp_f32_e32 v107, v107
	ds_read_b128 v[64:67], v189
	ds_read_b128 v[80:83], v189 offset:512
	s_waitcnt lgkmcnt(12)
	v_mfma_f32_32x32x16_bf16 v[4:19], v[156:159], v[68:71], v[4:19]
	v_exp_f32_e32 v108, v108
	v_exp_f32_e32 v109, v109
	v_exp_f32_e32 v110, v110
	v_exp_f32_e32 v111, v111
	ds_read_b128 v[164:167], v189 offset:2048
	ds_read_b128 v[168:171], v189 offset:2560
	s_waitcnt lgkmcnt(12)
	v_mfma_f32_32x32x16_bf16 v[20:35], v[156:159], v[72:75], v[20:35]
	v_exp_f32_e32 v112, v112
	v_exp_f32_e32 v113, v113
	v_exp_f32_e32 v114, v114
	v_exp_f32_e32 v115, v115
	ds_read_b128 v[172:175], v189 offset:4096
	ds_read_b128 v[176:179], v189 offset:4608
	s_waitcnt lgkmcnt(12)
	v_mfma_f32_32x32x16_bf16 v[4:19], v[148:151], v[76:79], v[4:19]
	v_exp_f32_e32 v84, v84
	v_exp_f32_e32 v85, v85
	v_exp_f32_e32 v86, v86
	v_exp_f32_e32 v87, v87
	ds_read_b128 v[198:201], v189 offset:6144
	ds_read_b128 v[72:75], v189 offset:6656
	s_waitcnt lgkmcnt(12)
	v_mfma_f32_32x32x16_bf16 v[20:35], v[148:151], v[52:55], v[20:35]
	v_exp_f32_e32 v88, v88
	v_exp_f32_e32 v89, v89
	v_exp_f32_e32 v90, v90
	v_exp_f32_e32 v91, v91
	s_waitcnt lgkmcnt(10)
	v_mfma_f32_32x32x16_bf16 v[4:19], v[140:143], v[56:59], v[4:19]
	v_exp_f32_e32 v92, v92
	v_exp_f32_e32 v93, v93
	v_exp_f32_e32 v94, v94
	v_exp_f32_e32 v95, v95
	s_waitcnt lgkmcnt(8)
	v_mfma_f32_32x32x16_bf16 v[20:35], v[140:143], v[60:63], v[20:35]
	v_exp_f32_e32 v96, v96
	v_exp_f32_e32 v97, v97
	v_exp_f32_e32 v98, v98
	v_exp_f32_e32 v99, v99
	s_waitcnt vmcnt(2) lgkmcnt(0)
	s_barrier
;   #define RESC() do{ if(resc){ asm volatile("s_waitcnt lgkmcnt(0)":::"memory"); \
;       _Pragma("unroll") for(int d_=0;d_<2;++d_) _Pragma("unroll") for(int r=0;r<16;++r)o[d_][r]*=wsf[crow(r,hi)]; } }while(0)
;   #define ROT() do{sl_prev=sl_cur;sl_cur=sl_next;sl_next=(sl_next==(NSLOT-1)*SLOTB)?0:sl_next+SLOTB;}while(0)
;   #define ENDW(tt) do{ if((tt)+3<NT){WAIT_BAR(2);} else if((tt)+2<NT){WAIT_BAR(1);} else {WAIT_BAR(0);} }while(0)
; template<int THRL,bool NOMAX> __device__ __forceinline__ void attn_unit(int b,int h,int qb,int t0,const bf16*Q,const bf16*__restrict__ KV,const bf16*__restrict__ GA,bf16*O,char*shm){
;     ...
;   for(;t+1<NT;t+=2){
;     STEP(pB0,pB1,pA0,pA1,t,(t+3<NT),(t+1<NT),(t+1<NT));       ENDW(t);   RESC(); ROT();
;     STEP(pA0,pA1,pB0,pB1,t+1,(t+4<NT),(t+2<NT),(t+2<NT));     ENDW(t+1); RESC(); ROT();
	ds_read_b64_tr_b16 v[202:203], v2 offset:40960
	ds_read_b64_tr_b16 v[204:205], v2 offset:41472
	v_add_f32_e32 v52, v100, v101
	v_add_f32_e32 v52, v102, v52
	v_add_f32_e32 v52, v103, v52
	v_add_f32_e32 v52, v104, v52
	v_add_f32_e32 v52, v105, v52
	v_cvt_pk_bf16_f32 v160, v100, v101
	v_cvt_pk_bf16_f32 v161, v102, v103
	s_waitcnt lgkmcnt(9)
	v_mfma_f32_32x32x16_bf16 v[116:131], v[64:67], v[152:155], v[36:51]
	ds_read_b64_tr_b16 v[100:101], v2 offset:45056
	ds_read_b64_tr_b16 v[102:103], v2 offset:45568
	v_add_f32_e32 v52, v106, v52
	v_add_f32_e32 v52, v107, v52
	v_add_f32_e32 v52, v108, v52
	v_add_f32_e32 v76, v109, v52
	v_cvt_pk_bf16_f32 v162, v104, v105
	v_cvt_pk_bf16_f32 v163, v106, v107
	s_waitcnt lgkmcnt(10)
	v_mfma_f32_32x32x16_bf16 v[52:67], v[80:83], v[152:155], v[36:51]
	ds_read_b64_tr_b16 v[68:69], v2 offset:41984
	ds_read_b64_tr_b16 v[70:71], v2 offset:42496
	v_add_f32_e32 v76, v110, v76
	v_add_f32_e32 v76, v111, v76
	v_add_f32_e32 v76, v112, v76
	v_add_f32_e32 v80, v113, v76
	v_cvt_pk_bf16_f32 v156, v108, v109
	v_cvt_pk_bf16_f32 v157, v110, v111
	s_waitcnt lgkmcnt(11)
	v_mfma_f32_32x32x16_bf16 v[116:131], v[164:167], v[144:147], v[116:131]
	ds_read_b64_tr_b16 v[76:77], v2 offset:46080
	ds_read_b64_tr_b16 v[78:79], v2 offset:46592
	v_add_f32_e32 v80, v114, v80
	v_add_f32_e32 v80, v115, v80
	v_add_f32_e32 v80, v84, v80
	v_add_f32_e32 v104, v85, v80
	v_cvt_pk_bf16_f32 v158, v112, v113
	v_cvt_pk_bf16_f32 v159, v114, v115
	s_waitcnt lgkmcnt(12)
	v_mfma_f32_32x32x16_bf16 v[52:67], v[168:171], v[144:147], v[52:67]
	ds_read_b64_tr_b16 v[80:81], v2 offset:43008
	ds_read_b64_tr_b16 v[82:83], v2 offset:43520
	v_add_f32_e32 v104, v86, v104
	v_add_f32_e32 v104, v87, v104
	v_add_f32_e32 v104, v88, v104
	v_add_f32_e32 v108, v89, v104
	v_cvt_pk_bf16_f32 v148, v84, v85
	v_cvt_pk_bf16_f32 v149, v86, v87
	s_waitcnt lgkmcnt(13)
	v_mfma_f32_32x32x16_bf16 v[116:131], v[172:175], v[136:139], v[116:131]
	ds_read_b64_tr_b16 v[104:105], v2 offset:47104
	ds_read_b64_tr_b16 v[106:107], v2 offset:47616
	v_add_f32_e32 v84, v90, v108
	v_add_f32_e32 v84, v91, v84
	v_add_f32_e32 v84, v92, v84
	v_add_f32_e32 v84, v93, v84
	v_cvt_pk_bf16_f32 v150, v88, v89
	v_cvt_pk_bf16_f32 v151, v90, v91
	s_waitcnt lgkmcnt(14)
	v_mfma_f32_32x32x16_bf16 v[52:67], v[176:179], v[136:139], v[52:67]
	ds_read_b64_tr_b16 v[88:89], v2 offset:44032
	ds_read_b64_tr_b16 v[90:91], v2 offset:44544
	v_add_f32_e32 v84, v94, v84
	v_add_f32_e32 v84, v95, v84
	v_add_f32_e32 v84, v96, v84
	v_add_f32_e32 v84, v97, v84
	v_cvt_pk_bf16_f32 v140, v92, v93
	v_cvt_pk_bf16_f32 v141, v94, v95
	s_waitcnt lgkmcnt(14)
	v_mfma_f32_32x32x16_bf16 v[116:131], v[198:201], v[132:135], v[116:131]
	ds_read_b64_tr_b16 v[92:93], v2 offset:48128
	ds_read_b64_tr_b16 v[94:95], v2 offset:48640
	v_mfma_f32_32x32x16_bf16 v[52:67], v[72:75], v[132:135], v[52:67]
	v_add_f32_e32 v72, v98, v84
	v_add_f32_e32 v72, v99, v72
	v_add_f32_e32 v72, 0, v72
	v_cvt_pk_bf16_f32 v142, v96, v97
	v_cvt_pk_bf16_f32 v143, v98, v99
	v_readlane_b32 s22, v254, 60
	v_readlane_b32 s23, v254, 61
	s_mov_b32 s23, s17
	v_add_f32_e32 v191, v191, v72
	v_lshl_add_u64 v[72:73], v[182:183], 0, s[22:23]
	s_mov_b32 s14, m0
	s_mov_b32 m0, s9
	s_nop 0
	global_load_lds_dwordx4 v[72:73], off
	s_mov_b32 m0, s14
	s_add_i32 s9, s13, 0x8000
	v_readlane_b32 s14, v254, 62
	v_readlane_b32 s15, v254, 63
	s_mov_b32 s15, s17
	s_mov_b32 s16, s14
	v_lshl_add_u64 v[72:73], v[180:181], 0, s[14:15]
	s_mov_b32 s14, m0
	s_mov_b32 m0, s9
	s_nop 0
	global_load_lds_dwordx4 v[72:73], off
	s_mov_b32 m0, s14
	v_writelane_b32 v254, s16, 62
	s_nop 1
	v_writelane_b32 v254, s17, 63
	s_waitcnt lgkmcnt(14)
	v_mfma_f32_32x32x16_bf16 v[4:19], v[160:163], v[202:205], v[4:19]
	v_exp_f32_e32 v116, v116
	v_exp_f32_e32 v117, v117
	v_exp_f32_e32 v118, v118
	v_exp_f32_e32 v119, v119
	s_waitcnt lgkmcnt(12)
	v_mfma_f32_32x32x16_bf16 v[20:35], v[160:163], v[100:103], v[20:35]
	v_exp_f32_e32 v120, v120
	v_exp_f32_e32 v121, v121
	v_exp_f32_e32 v122, v122
	v_exp_f32_e32 v123, v123
	ds_read_b128 v[72:75], v189 offset:8192
	ds_read_b128 v[96:99], v189 offset:8704
	s_waitcnt lgkmcnt(12)
	v_mfma_f32_32x32x16_bf16 v[4:19], v[156:159], v[68:71], v[4:19]
	v_exp_f32_e32 v124, v124
	v_exp_f32_e32 v125, v125
	v_exp_f32_e32 v126, v126
	v_exp_f32_e32 v127, v127
	ds_read_b128 v[164:167], v189 offset:10240
	ds_read_b128 v[168:171], v189 offset:10752
	s_waitcnt lgkmcnt(12)
	v_mfma_f32_32x32x16_bf16 v[20:35], v[156:159], v[76:79], v[20:35]
	v_exp_f32_e32 v128, v128
	v_exp_f32_e32 v129, v129
	v_exp_f32_e32 v130, v130
	v_exp_f32_e32 v131, v131
	ds_read_b128 v[172:175], v189 offset:12288
	ds_read_b128 v[176:179], v189 offset:12800
	s_waitcnt lgkmcnt(12)
	v_mfma_f32_32x32x16_bf16 v[4:19], v[148:151], v[80:83], v[4:19]
	v_exp_f32_e32 v52, v52
	v_exp_f32_e32 v53, v53
	v_exp_f32_e32 v54, v54
	v_exp_f32_e32 v55, v55
	ds_read_b128 v[198:201], v189 offset:14336
	ds_read_b128 v[84:87], v189 offset:14848
	s_waitcnt lgkmcnt(12)
	v_mfma_f32_32x32x16_bf16 v[20:35], v[148:151], v[104:107], v[20:35]
	v_exp_f32_e32 v56, v56
	v_exp_f32_e32 v57, v57
	v_exp_f32_e32 v58, v58
	v_exp_f32_e32 v59, v59
	s_waitcnt lgkmcnt(10)
	v_mfma_f32_32x32x16_bf16 v[4:19], v[140:143], v[88:91], v[4:19]
	v_exp_f32_e32 v60, v60
	v_exp_f32_e32 v61, v61
	v_exp_f32_e32 v62, v62
	v_exp_f32_e32 v63, v63
	s_waitcnt lgkmcnt(8)
	v_mfma_f32_32x32x16_bf16 v[20:35], v[140:143], v[92:95], v[20:35]
	v_exp_f32_e32 v64, v64
	v_exp_f32_e32 v65, v65
	v_exp_f32_e32 v66, v66
	v_exp_f32_e32 v67, v67
	s_waitcnt vmcnt(2) lgkmcnt(0)
	s_barrier
; template<int THRL,bool NOMAX> __device__ __forceinline__ void attn_unit(int b,int h,int qb,int t0,const bf16*Q,const bf16*__restrict__ KV,const bf16*__restrict__ GA,bf16*O,char*shm){
;     ...
;   bf16*Ow=O+(rowbase+q0+wid*QBLK)*QP+h*D; const bf16*Gw=GA+(rowbase+q0+wid*QBLK)*GP+h*D;
;   u32x4 gpre[4];
;   #pragma unroll
;   for(int i=0;i<4;++i)gpre[i]=*(const u32x4*)(Gw+(long)(i*8+(lane>>3))*GP+(lane&7)*8);
	s_lshl_b64 s[98:99], s[4:5], 1
	s_add_u32 s98, s84, s98
	s_addc_u32 s99, s85, s99
	s_add_u32 s98, s98, s6
	s_addc_u32 s99, s99, s7
	v_and_b32_e32 v192, 56, v187
	v_lshlrev_b32_e32 v193, 8, v184
	v_lshlrev_b32_e32 v192, 1, v192
	v_and_b32_e32 v193, 0x3800, v193
	v_add_u32_e32 v192, v192, v193
	global_load_dwordx4 v[206:209], v192, s[98:99]
	s_add_u32 s98, s98, 0x4000
	s_addc_u32 s99, s99, 0
	global_load_dwordx4 v[210:213], v192, s[98:99]
	s_add_u32 s98, s98, 0x4000
	s_addc_u32 s99, s99, 0
	global_load_dwordx4 v[214:217], v192, s[98:99]
	s_add_u32 s98, s98, 0x4000
	s_addc_u32 s99, s99, 0
	global_load_dwordx4 v[218:221], v192, s[98:99]
	ds_read_b64_tr_b16 v[88:89], v2 offset:24576
	ds_read_b64_tr_b16 v[90:91], v2 offset:25088
	v_add_f32_e32 v68, v116, v117
	v_add_f32_e32 v68, v118, v68
	v_add_f32_e32 v68, v119, v68
	v_add_f32_e32 v68, v120, v68
	v_add_f32_e32 v68, v121, v68
	v_cvt_pk_bf16_f32 v160, v116, v117
	v_cvt_pk_bf16_f32 v161, v118, v119
	s_waitcnt lgkmcnt(9)
	v_mfma_f32_32x32x16_bf16 v[100:115], v[72:75], v[152:155], v[36:51]
	ds_read_b64_tr_b16 v[92:93], v2 offset:28672
	ds_read_b64_tr_b16 v[94:95], v2 offset:29184
	v_add_f32_e32 v68, v122, v68
	v_add_f32_e32 v68, v123, v68
	v_add_f32_e32 v68, v124, v68
	v_add_f32_e32 v116, v125, v68
	v_cvt_pk_bf16_f32 v162, v120, v121
	v_cvt_pk_bf16_f32 v163, v122, v123
	s_waitcnt lgkmcnt(10)
	v_mfma_f32_32x32x16_bf16 v[68:83], v[96:99], v[152:155], v[36:51]
	ds_read_b64_tr_b16 v[96:97], v2 offset:25600
	ds_read_b64_tr_b16 v[98:99], v2 offset:26112
	v_add_f32_e32 v116, v126, v116
	v_add_f32_e32 v116, v127, v116
	v_add_f32_e32 v116, v128, v116
	v_add_f32_e32 v120, v129, v116
	v_cvt_pk_bf16_f32 v156, v124, v125
	v_cvt_pk_bf16_f32 v157, v126, v127
	s_waitcnt lgkmcnt(11)
	v_mfma_f32_32x32x16_bf16 v[100:115], v[164:167], v[144:147], v[100:115]
	ds_read_b64_tr_b16 v[116:117], v2 offset:29696
	ds_read_b64_tr_b16 v[118:119], v2 offset:30208
	v_add_f32_e32 v120, v130, v120
	v_add_f32_e32 v120, v131, v120
	v_add_f32_e32 v120, v52, v120
	v_add_f32_e32 v124, v53, v120
	v_cvt_pk_bf16_f32 v158, v128, v129
	v_cvt_pk_bf16_f32 v159, v130, v131
	s_waitcnt lgkmcnt(12)
	v_mfma_f32_32x32x16_bf16 v[68:83], v[168:171], v[144:147], v[68:83]
	ds_read_b64_tr_b16 v[120:121], v2 offset:26624
	ds_read_b64_tr_b16 v[122:123], v2 offset:27136
	v_add_f32_e32 v124, v54, v124
	v_add_f32_e32 v124, v55, v124
	v_add_f32_e32 v124, v56, v124
	v_add_f32_e32 v124, v57, v124
	v_cvt_pk_bf16_f32 v148, v52, v53
	v_cvt_pk_bf16_f32 v149, v54, v55
	s_waitcnt lgkmcnt(13)
	v_mfma_f32_32x32x16_bf16 v[100:115], v[172:175], v[136:139], v[100:115]
	ds_read_b64_tr_b16 v[52:53], v2 offset:30720
	ds_read_b64_tr_b16 v[54:55], v2 offset:31232
	v_add_f32_e32 v124, v58, v124
	v_add_f32_e32 v124, v59, v124
	v_add_f32_e32 v124, v60, v124
	v_add_f32_e32 v124, v61, v124
	v_cvt_pk_bf16_f32 v150, v56, v57
	v_cvt_pk_bf16_f32 v151, v58, v59
	s_waitcnt lgkmcnt(14)
	v_mfma_f32_32x32x16_bf16 v[68:83], v[176:179], v[136:139], v[68:83]
	ds_read_b64_tr_b16 v[56:57], v2 offset:27648
	ds_read_b64_tr_b16 v[58:59], v2 offset:28160
	v_add_f32_e32 v124, v62, v124
	v_add_f32_e32 v124, v63, v124
	v_add_f32_e32 v124, v64, v124
	v_add_f32_e32 v124, v65, v124
	v_cvt_pk_bf16_f32 v140, v60, v61
	v_cvt_pk_bf16_f32 v141, v62, v63
	s_waitcnt lgkmcnt(14)
	v_mfma_f32_32x32x16_bf16 v[100:115], v[198:201], v[132:135], v[100:115]
	ds_read_b64_tr_b16 v[60:61], v2 offset:31744
	ds_read_b64_tr_b16 v[62:63], v2 offset:32256
	v_mfma_f32_32x32x16_bf16 v[68:83], v[84:87], v[132:135], v[68:83]
	v_add_f32_e32 v84, v66, v124
	v_add_f32_e32 v84, v67, v84
	v_add_f32_e32 v84, 0, v84
	v_cvt_pk_bf16_f32 v142, v64, v65
	v_cvt_pk_bf16_f32 v143, v66, v67
	s_mov_b32 s14, s20
	v_lshl_add_u64 v[64:65], v[180:181], 0, s[20:21]
	s_add_i32 s13, s13, 0xa000
	s_mov_b32 s9, m0
	s_mov_b32 m0, s13
	s_nop 0
	global_load_lds_dwordx4 v[64:65], off
	s_mov_b32 m0, s9
	v_writelane_b32 v254, s14, 56
	v_add_f32_e32 v182, v191, v84
	s_nop 0
	v_writelane_b32 v254, s15, 57
	s_waitcnt lgkmcnt(14)
	v_mfma_f32_32x32x16_bf16 v[4:19], v[160:163], v[88:91], v[4:19]
	v_exp_f32_e32 v100, v100
	v_exp_f32_e32 v101, v101
	v_exp_f32_e32 v102, v102
	v_exp_f32_e32 v103, v103
	s_waitcnt lgkmcnt(12)
	v_mfma_f32_32x32x16_bf16 v[20:35], v[160:163], v[92:95], v[20:35]
	v_exp_f32_e32 v104, v104
	v_exp_f32_e32 v105, v105
	v_exp_f32_e32 v106, v106
	v_exp_f32_e32 v107, v107
	ds_read_b128 v[64:67], v189 offset:16384
	ds_read_b128 v[124:127], v189 offset:16896
	s_waitcnt lgkmcnt(12)
	v_mfma_f32_32x32x16_bf16 v[4:19], v[156:159], v[96:99], v[4:19]
	v_exp_f32_e32 v108, v108
	v_exp_f32_e32 v109, v109
	v_exp_f32_e32 v110, v110
	v_exp_f32_e32 v111, v111
	ds_read_b128 v[128:131], v189 offset:18432
	ds_read_b128 v[164:167], v189 offset:18944
	s_waitcnt lgkmcnt(12)
	v_mfma_f32_32x32x16_bf16 v[20:35], v[156:159], v[116:119], v[20:35]
	v_exp_f32_e32 v112, v112
	v_exp_f32_e32 v113, v113
	v_exp_f32_e32 v114, v114
	v_exp_f32_e32 v115, v115
	ds_read_b128 v[168:171], v189 offset:20480
	ds_read_b128 v[172:175], v189 offset:20992
	s_waitcnt lgkmcnt(12)
	v_mfma_f32_32x32x16_bf16 v[4:19], v[148:151], v[120:123], v[4:19]
	v_exp_f32_e32 v68, v68
	v_exp_f32_e32 v69, v69
	v_exp_f32_e32 v70, v70
	v_exp_f32_e32 v71, v71
	ds_read_b128 v[120:123], v189 offset:22528
	ds_read_b128 v[116:119], v189 offset:23040
	s_waitcnt lgkmcnt(12)
	v_mfma_f32_32x32x16_bf16 v[20:35], v[148:151], v[52:55], v[20:35]
	v_exp_f32_e32 v72, v72
	v_exp_f32_e32 v73, v73
	v_exp_f32_e32 v74, v74
	v_exp_f32_e32 v75, v75
	s_waitcnt lgkmcnt(10)
	v_mfma_f32_32x32x16_bf16 v[4:19], v[140:143], v[56:59], v[4:19]
	v_exp_f32_e32 v76, v76
	v_exp_f32_e32 v77, v77
	v_exp_f32_e32 v78, v78
	v_exp_f32_e32 v79, v79
	s_waitcnt lgkmcnt(8)
	v_mfma_f32_32x32x16_bf16 v[20:35], v[140:143], v[60:63], v[20:35]
	v_exp_f32_e32 v80, v80
	v_exp_f32_e32 v81, v81
	v_exp_f32_e32 v82, v82
	v_exp_f32_e32 v83, v83
	s_waitcnt vmcnt(5) lgkmcnt(0)
	s_barrier
;   #define RESC() do{ if(resc){ asm volatile("s_waitcnt lgkmcnt(0)":::"memory"); \
;       _Pragma("unroll") for(int d_=0;d_<2;++d_) _Pragma("unroll") for(int r=0;r<16;++r)o[d_][r]*=wsf[crow(r,hi)]; } }while(0)
;   #define ROT() do{sl_prev=sl_cur;sl_cur=sl_next;sl_next=(sl_next==(NSLOT-1)*SLOTB)?0:sl_next+SLOTB;}while(0)
;   #define ENDW(tt) do{ if((tt)+3<NT){WAIT_BAR(2);} else if((tt)+2<NT){WAIT_BAR(1);} else {WAIT_BAR(0);} }while(0)
; template<int THRL,bool NOMAX> __device__ __forceinline__ void attn_unit(int b,int h,int qb,int t0,const bf16*Q,const bf16*__restrict__ KV,const bf16*__restrict__ GA,bf16*O,char*shm){
;     ...
;   for(;t+1<NT;t+=2){
;     STEP(pB0,pB1,pA0,pA1,t,(t+3<NT),(t+1<NT),(t+1<NT));       ENDW(t);   RESC(); ROT();
;     STEP(pA0,pA1,pB0,pB1,t+1,(t+4<NT),(t+2<NT),(t+2<NT));     ENDW(t+1); RESC(); ROT();
	ds_read_b64_tr_b16 v[176:177], v2 offset:32768
	ds_read_b64_tr_b16 v[178:179], v2 offset:33280
	v_add_f32_e32 v52, v100, v101
	v_add_f32_e32 v52, v102, v52
	v_add_f32_e32 v52, v103, v52
	v_add_f32_e32 v52, v104, v52
	v_add_f32_e32 v52, v105, v52
	v_cvt_pk_bf16_f32 v160, v100, v101
	v_cvt_pk_bf16_f32 v161, v102, v103
	s_waitcnt lgkmcnt(9)
	v_mfma_f32_32x32x16_bf16 v[84:99], v[64:67], v[152:155], v[36:51]
	ds_read_b64_tr_b16 v[100:101], v2 offset:36864
	ds_read_b64_tr_b16 v[102:103], v2 offset:37376
	v_add_f32_e32 v52, v106, v52
	v_add_f32_e32 v52, v107, v52
	v_add_f32_e32 v52, v108, v52
	v_add_f32_e32 v140, v109, v52
	v_cvt_pk_bf16_f32 v162, v104, v105
	v_cvt_pk_bf16_f32 v163, v106, v107
	s_waitcnt lgkmcnt(10)
	v_mfma_f32_32x32x16_bf16 v[52:67], v[124:127], v[152:155], v[36:51]
	ds_read_b64_tr_b16 v[124:125], v2 offset:33792
	ds_read_b64_tr_b16 v[126:127], v2 offset:34304
	v_add_f32_e32 v104, v110, v140
	v_add_f32_e32 v104, v111, v104
	v_add_f32_e32 v104, v112, v104
	v_add_f32_e32 v104, v113, v104
	v_cvt_pk_bf16_f32 v156, v108, v109
	v_cvt_pk_bf16_f32 v157, v110, v111
	s_waitcnt lgkmcnt(11)
	v_mfma_f32_32x32x16_bf16 v[84:99], v[128:131], v[144:147], v[84:99]
	ds_read_b64_tr_b16 v[106:107], v2 offset:37888
	ds_read_b64_tr_b16 v[108:109], v2 offset:38400
	v_add_f32_e32 v104, v114, v104
	v_add_f32_e32 v104, v115, v104
	v_add_f32_e32 v104, v68, v104
	v_add_f32_e32 v104, v69, v104
	v_cvt_pk_bf16_f32 v158, v112, v113
	v_cvt_pk_bf16_f32 v159, v114, v115
	s_waitcnt lgkmcnt(12)
	v_mfma_f32_32x32x16_bf16 v[52:67], v[164:167], v[144:147], v[52:67]
	ds_read_b64_tr_b16 v[110:111], v2 offset:34816
	ds_read_b64_tr_b16 v[112:113], v2 offset:35328
	v_add_f32_e32 v104, v70, v104
	v_add_f32_e32 v104, v71, v104
	v_add_f32_e32 v104, v72, v104
	v_add_f32_e32 v104, v73, v104
	v_cvt_pk_bf16_f32 v148, v68, v69
	v_cvt_pk_bf16_f32 v149, v70, v71
	s_waitcnt lgkmcnt(13)
	v_mfma_f32_32x32x16_bf16 v[84:99], v[168:171], v[136:139], v[84:99]
	ds_read_b64_tr_b16 v[68:69], v2 offset:38912
	ds_read_b64_tr_b16 v[70:71], v2 offset:39424
	v_add_f32_e32 v104, v74, v104
	v_add_f32_e32 v104, v75, v104
	v_add_f32_e32 v104, v76, v104
	v_add_f32_e32 v104, v77, v104
	v_cvt_pk_bf16_f32 v150, v72, v73
	v_cvt_pk_bf16_f32 v151, v74, v75
	s_waitcnt lgkmcnt(14)
	v_mfma_f32_32x32x16_bf16 v[52:67], v[172:175], v[136:139], v[52:67]
	ds_read_b64_tr_b16 v[72:73], v2 offset:35840
	ds_read_b64_tr_b16 v[74:75], v2 offset:36352
	v_add_f32_e32 v104, v78, v104
	v_add_f32_e32 v104, v79, v104
	v_add_f32_e32 v104, v80, v104
	v_add_f32_e32 v104, v81, v104
	v_cvt_pk_bf16_f32 v140, v76, v77
	v_cvt_pk_bf16_f32 v141, v78, v79
	s_waitcnt lgkmcnt(14)
	v_mfma_f32_32x32x16_bf16 v[84:99], v[120:123], v[132:135], v[84:99]
	ds_read_b64_tr_b16 v[76:77], v2 offset:39936
	ds_read_b64_tr_b16 v[78:79], v2 offset:40448
	v_add_f32_e32 v104, v82, v104
	v_add_f32_e32 v104, v83, v104
	v_add_f32_e32 v104, 0, v104
	v_cvt_pk_bf16_f32 v142, v80, v81
	v_cvt_pk_bf16_f32 v143, v82, v83
	v_mfma_f32_32x32x16_bf16 v[52:67], v[116:119], v[132:135], v[52:67]
	s_mov_b32 s14, s22
	v_lshl_add_u64 v[80:81], v[180:181], 0, s[22:23]
	s_mov_b32 s9, m0
	s_mov_b32 m0, s8
	s_nop 0
	global_load_lds_dwordx4 v[80:81], off
	s_mov_b32 m0, s9
	v_writelane_b32 v254, s14, 60
	v_add_f32_e32 v104, v182, v104
	s_nop 0
	v_writelane_b32 v254, s15, 61
	s_waitcnt lgkmcnt(14)
	v_mfma_f32_32x32x16_bf16 v[4:19], v[160:163], v[176:179], v[4:19]
	v_exp_f32_e32 v84, v84
	v_exp_f32_e32 v85, v85
	v_exp_f32_e32 v86, v86
	v_exp_f32_e32 v87, v87
	s_waitcnt lgkmcnt(12)
	v_mfma_f32_32x32x16_bf16 v[20:35], v[160:163], v[100:103], v[20:35]
	v_exp_f32_e32 v88, v88
	v_exp_f32_e32 v89, v89
	v_exp_f32_e32 v90, v90
	v_exp_f32_e32 v91, v91
	ds_read_b128 v[114:117], v189
	ds_read_b128 v[118:121], v189 offset:512
	s_waitcnt lgkmcnt(12)
	v_mfma_f32_32x32x16_bf16 v[4:19], v[156:159], v[124:127], v[4:19]
	v_exp_f32_e32 v92, v92
	v_exp_f32_e32 v93, v93
	v_exp_f32_e32 v94, v94
	v_exp_f32_e32 v95, v95
	ds_read_b128 v[122:125], v189 offset:2048
	ds_read_b128 v[126:129], v189 offset:2560
	s_waitcnt lgkmcnt(12)
	v_mfma_f32_32x32x16_bf16 v[20:35], v[156:159], v[106:109], v[20:35]
	v_exp_f32_e32 v96, v96
	v_exp_f32_e32 v97, v97
	v_exp_f32_e32 v98, v98
	v_exp_f32_e32 v99, v99
	ds_read_b128 v[106:109], v189 offset:4096
	ds_read_b128 v[164:167], v189 offset:4608
	s_waitcnt lgkmcnt(12)
	v_mfma_f32_32x32x16_bf16 v[4:19], v[148:151], v[110:113], v[4:19]
	v_exp_f32_e32 v52, v52
	v_exp_f32_e32 v53, v53
	v_exp_f32_e32 v54, v54
	v_exp_f32_e32 v55, v55
	ds_read_b128 v[110:113], v189 offset:6144
	ds_read_b128 v[100:103], v189 offset:6656
	s_waitcnt lgkmcnt(12)
	v_mfma_f32_32x32x16_bf16 v[20:35], v[148:151], v[68:71], v[20:35]
	v_exp_f32_e32 v56, v56
	v_exp_f32_e32 v57, v57
	v_exp_f32_e32 v58, v58
	v_exp_f32_e32 v59, v59
	s_waitcnt lgkmcnt(10)
	v_mfma_f32_32x32x16_bf16 v[4:19], v[140:143], v[72:75], v[4:19]
	v_exp_f32_e32 v60, v60
	v_exp_f32_e32 v61, v61
	v_exp_f32_e32 v62, v62
	v_exp_f32_e32 v63, v63
	s_waitcnt lgkmcnt(8)
	v_mfma_f32_32x32x16_bf16 v[20:35], v[140:143], v[76:79], v[20:35]
	v_exp_f32_e32 v64, v64
	v_exp_f32_e32 v65, v65
	v_exp_f32_e32 v66, v66
	v_exp_f32_e32 v67, v67
	s_waitcnt vmcnt(0) lgkmcnt(0)
	s_barrier
;   #define RESC() do{ if(resc){ asm volatile("s_waitcnt lgkmcnt(0)":::"memory"); \
;       _Pragma("unroll") for(int d_=0;d_<2;++d_) _Pragma("unroll") for(int r=0;r<16;++r)o[d_][r]*=wsf[crow(r,hi)]; } }while(0)
; template<int THRL,bool NOMAX> __device__ __forceinline__ void attn_unit(int b,int h,int qb,int t0,const bf16*Q,const bf16*__restrict__ KV,const bf16*__restrict__ GA,bf16*O,char*shm){
;     ...
;   STEP(pB0,pB1,pA0,pA1,NT-1,false,false,false); RESC();
	ds_read_b64_tr_b16 v[168:169], v2 offset:40960
	ds_read_b64_tr_b16 v[170:171], v2 offset:41472
	v_add_f32_e32 v68, v84, v85
	v_add_f32_e32 v68, v86, v68
	v_add_f32_e32 v68, v87, v68
	v_add_f32_e32 v68, v88, v68
	v_add_f32_e32 v105, v89, v68
	v_cvt_pk_bf16_f32 v160, v84, v85
	v_cvt_pk_bf16_f32 v161, v86, v87
	s_waitcnt lgkmcnt(9)
	v_mfma_f32_32x32x16_bf16 v[68:83], v[114:117], v[152:155], v[36:51]
	ds_read_b64_tr_b16 v[84:85], v2 offset:45056
	ds_read_b64_tr_b16 v[86:87], v2 offset:45568
	s_waitcnt lgkmcnt(10)
	v_mfma_f32_32x32x16_bf16 v[36:51], v[118:121], v[152:155], v[36:51]
	v_add_f32_e32 v105, v90, v105
	v_add_f32_e32 v105, v91, v105
	v_add_f32_e32 v105, v92, v105
	v_add_f32_e32 v105, v93, v105
	v_cvt_pk_bf16_f32 v162, v88, v89
	v_cvt_pk_bf16_f32 v163, v90, v91
	ds_read_b64_tr_b16 v[88:89], v2 offset:41984
	ds_read_b64_tr_b16 v[90:91], v2 offset:42496
	v_add_f32_e32 v105, v94, v105
	v_add_f32_e32 v105, v95, v105
	v_add_f32_e32 v105, v96, v105
	v_add_f32_e32 v105, v97, v105
	v_cvt_pk_bf16_f32 v156, v92, v93
	v_cvt_pk_bf16_f32 v157, v94, v95
	s_waitcnt lgkmcnt(11)
	v_mfma_f32_32x32x16_bf16 v[68:83], v[122:125], v[144:147], v[68:83]
	ds_read_b64_tr_b16 v[92:93], v2 offset:46080
	ds_read_b64_tr_b16 v[94:95], v2 offset:46592
	s_waitcnt lgkmcnt(12)
	v_mfma_f32_32x32x16_bf16 v[36:51], v[126:129], v[144:147], v[36:51]
	v_add_f32_e32 v105, v98, v105
	v_add_f32_e32 v105, v99, v105
	v_add_f32_e32 v105, v52, v105
	v_add_f32_e32 v105, v53, v105
	v_cvt_pk_bf16_f32 v158, v96, v97
	v_cvt_pk_bf16_f32 v159, v98, v99
	ds_read_b64_tr_b16 v[96:97], v2 offset:43008
	ds_read_b64_tr_b16 v[98:99], v2 offset:43520
	v_add_f32_e32 v105, v54, v105
	v_add_f32_e32 v105, v55, v105
	v_add_f32_e32 v105, v56, v105
	v_add_f32_e32 v105, v57, v105
	v_cvt_pk_bf16_f32 v148, v52, v53
	v_cvt_pk_bf16_f32 v149, v54, v55
	s_waitcnt lgkmcnt(13)
	v_mfma_f32_32x32x16_bf16 v[68:83], v[106:109], v[136:139], v[68:83]
	ds_read_b64_tr_b16 v[52:53], v2 offset:47104
	ds_read_b64_tr_b16 v[54:55], v2 offset:47616
	s_waitcnt lgkmcnt(14)
	v_mfma_f32_32x32x16_bf16 v[36:51], v[164:167], v[136:139], v[36:51]
	v_add_f32_e32 v105, v58, v105
	v_add_f32_e32 v105, v59, v105
	v_add_f32_e32 v105, v60, v105
	v_add_f32_e32 v105, v61, v105
	v_cvt_pk_bf16_f32 v150, v56, v57
	v_cvt_pk_bf16_f32 v151, v58, v59
	ds_read_b64_tr_b16 v[56:57], v2 offset:44032
	ds_read_b64_tr_b16 v[58:59], v2 offset:44544
	v_add_f32_e32 v105, v62, v105
	v_add_f32_e32 v105, v63, v105
	v_add_f32_e32 v105, v64, v105
	v_add_f32_e32 v105, v65, v105
	v_cvt_pk_bf16_f32 v140, v60, v61
	v_cvt_pk_bf16_f32 v141, v62, v63
	s_waitcnt lgkmcnt(14)
	v_mfma_f32_32x32x16_bf16 v[68:83], v[110:113], v[132:135], v[68:83]
	ds_read_b64_tr_b16 v[60:61], v2 offset:48128
	ds_read_b64_tr_b16 v[62:63], v2 offset:48640
	v_mfma_f32_32x32x16_bf16 v[36:51], v[100:103], v[132:135], v[36:51]
	v_add_f32_e32 v2, v66, v105
	v_add_f32_e32 v2, v67, v2
	v_add_f32_e32 v2, 0, v2
	v_cvt_pk_bf16_f32 v142, v64, v65
	v_cvt_pk_bf16_f32 v143, v66, v67
	s_waitcnt lgkmcnt(14)
	v_mfma_f32_32x32x16_bf16 v[4:19], v[160:163], v[168:171], v[4:19]
	s_nop 1
	v_exp_f32_e32 v68, v68
	v_exp_f32_e32 v69, v69
	v_exp_f32_e32 v70, v70
	v_exp_f32_e32 v71, v71
	s_waitcnt lgkmcnt(12)
	v_mfma_f32_32x32x16_bf16 v[20:35], v[160:163], v[84:87], v[20:35]
	v_exp_f32_e32 v72, v72
	v_exp_f32_e32 v73, v73
	v_exp_f32_e32 v74, v74
	v_exp_f32_e32 v75, v75
	s_waitcnt lgkmcnt(10)
	v_mfma_f32_32x32x16_bf16 v[4:19], v[156:159], v[88:91], v[4:19]
	v_exp_f32_e32 v76, v76
	v_exp_f32_e32 v77, v77
	v_exp_f32_e32 v78, v78
	v_exp_f32_e32 v79, v79
	s_waitcnt lgkmcnt(8)
	v_mfma_f32_32x32x16_bf16 v[20:35], v[156:159], v[92:95], v[20:35]
	v_exp_f32_e32 v80, v80
	v_exp_f32_e32 v81, v81
	v_exp_f32_e32 v82, v82
	v_exp_f32_e32 v83, v83
	s_waitcnt lgkmcnt(6)
; #define SBAR() __builtin_amdgcn_sched_barrier(0)
;   #define RESC() do{ if(resc){ asm volatile("s_waitcnt lgkmcnt(0)":::"memory"); \
;       _Pragma("unroll") for(int d_=0;d_<2;++d_) _Pragma("unroll") for(int r=0;r<16;++r)o[d_][r]*=wsf[crow(r,hi)]; } }while(0)
;   #define PKW(P,B) cvtpk_s(P[B],P[B+1])
; template<int THRL,bool NOMAX> __device__ __forceinline__ void attn_unit(int b,int h,int qb,int t0,const bf16*Q,const bf16*__restrict__ KV,const bf16*__restrict__ GA,bf16*O,char*shm){
;     ...
;   STEP(pB0,pB1,pA0,pA1,NT-1,false,false,false); RESC();
;   { float sacc=pB0[0]+pB0[1]; _Pragma("unroll") for(int r=2;r<16;++r)sacc+=pB0[r]; _Pragma("unroll") for(int r=0;r<16;++r)sacc+=pB1[r]; l_reg+=sacc;
;     pw0=(u32x4){PKW(pB0,0),PKW(pB0,2),PKW(pB0,4),PKW(pB0,6)};pw1=(u32x4){PKW(pB0,8),PKW(pB0,10),PKW(pB0,12),PKW(pB0,14)};pw2=(u32x4){PKW(pB1,0),PKW(pB1,2),PKW(pB1,4),PKW(pB1,6)};pw3=(u32x4){PKW(pB1,8),PKW(pB1,10),PKW(pB1,12),PKW(pB1,14)};
;     SBAR(); pv(o,vb0+sl_cur,PAF(0),PAF(1),PAF(2),PAF(3)); }
;     ...
;   {auto rr=__builtin_amdgcn_permlane32_swap(__float_as_uint(l_reg),__float_as_uint(l_reg),false,false);l_reg=__uint_as_float(rr[0])+__uint_as_float(rr[1]);}
;   if(hi==0)wsf[32+r32]=l_reg;asm volatile("s_waitcnt lgkmcnt(0)":::"memory");
	v_mfma_f32_32x32x16_bf16 v[4:19], v[148:151], v[96:99], v[4:19]
	v_exp_f32_e32 v36, v36
	v_exp_f32_e32 v37, v37
	v_exp_f32_e32 v38, v38
	v_exp_f32_e32 v39, v39
	s_waitcnt lgkmcnt(4)
	v_mfma_f32_32x32x16_bf16 v[20:35], v[148:151], v[52:55], v[20:35]
	v_exp_f32_e32 v40, v40
	v_exp_f32_e32 v41, v41
	v_exp_f32_e32 v42, v42
	v_exp_f32_e32 v43, v43
	s_waitcnt lgkmcnt(2)
	v_mfma_f32_32x32x16_bf16 v[4:19], v[140:143], v[56:59], v[4:19]
	v_exp_f32_e32 v44, v44
	v_exp_f32_e32 v45, v45
	v_exp_f32_e32 v46, v46
	v_exp_f32_e32 v47, v47
	s_waitcnt lgkmcnt(0)
	v_mfma_f32_32x32x16_bf16 v[20:35], v[140:143], v[60:63], v[20:35]
	v_exp_f32_e32 v48, v48
	v_exp_f32_e32 v49, v49
	v_exp_f32_e32 v50, v50
	v_exp_f32_e32 v51, v51
	v_add_f32_e32 v52, v68, v69
	v_add_f32_e32 v52, v70, v52
	v_add_f32_e32 v52, v71, v52
	v_add_f32_e32 v52, v72, v52
	v_add_f32_e32 v52, v73, v52
	v_add_f32_e32 v52, v74, v52
	v_add_f32_e32 v52, v75, v52
	v_add_f32_e32 v52, v76, v52
	v_add_f32_e32 v52, v77, v52
	v_add_f32_e32 v52, v78, v52
	v_add_f32_e32 v52, v79, v52
	v_add_f32_e32 v52, v80, v52
	v_add_f32_e32 v52, v81, v52
	v_add_f32_e32 v52, v82, v52
	v_add_f32_e32 v52, v83, v52
	v_add_f32_e32 v52, v36, v52
	v_add_f32_e32 v52, v37, v52
	v_add_f32_e32 v52, v38, v52
	v_add_f32_e32 v52, v39, v52
	v_add_f32_e32 v52, v40, v52
	v_add_f32_e32 v52, v41, v52
	v_add_f32_e32 v52, v42, v52
	v_add_f32_e32 v52, v43, v52
	v_add_f32_e32 v52, v44, v52
	v_add_f32_e32 v52, v45, v52
	v_add_f32_e32 v52, v46, v52
	v_add_f32_e32 v52, v47, v52
	v_add_f32_e32 v52, v48, v52
	v_add_f32_e32 v52, v49, v52
	v_add_f32_e32 v52, v50, v52
	v_add_f32_e32 v52, v51, v52
	v_add_f32_e32 v2, v104, v2
	v_add_f32_e32 v2, v2, v52
	v_cvt_pk_bf16_f32 v36, v36, v37
	v_cvt_pk_bf16_f32 v52, v68, v69
	v_cvt_pk_bf16_f32 v53, v70, v71
	v_cvt_pk_bf16_f32 v54, v72, v73
	v_cvt_pk_bf16_f32 v55, v74, v75
	v_cvt_pk_bf16_f32 v56, v76, v77
	v_cvt_pk_bf16_f32 v57, v78, v79
	v_cvt_pk_bf16_f32 v58, v80, v81
	v_cvt_pk_bf16_f32 v59, v82, v83
	v_cvt_pk_bf16_f32 v37, v38, v39
	v_cvt_pk_bf16_f32 v38, v40, v41
	v_cvt_pk_bf16_f32 v39, v42, v43
	v_cvt_pk_bf16_f32 v40, v44, v45
	v_cvt_pk_bf16_f32 v41, v46, v47
	v_cvt_pk_bf16_f32 v42, v48, v49
	v_cvt_pk_bf16_f32 v43, v50, v51
	ds_read_b64_tr_b16 v[44:45],v190 offset:0
	ds_read_b64_tr_b16 v[46:47],v190 offset:512
	ds_read_b64_tr_b16 v[48:49],v190 offset:1024
	ds_read_b64_tr_b16 v[50:51],v190 offset:1536
	ds_read_b64_tr_b16 v[60:61],v190 offset:2048
	ds_read_b64_tr_b16 v[62:63],v190 offset:2560
	ds_read_b64_tr_b16 v[64:65],v190 offset:3072
	ds_read_b64_tr_b16 v[66:67],v190 offset:3584
	s_waitcnt lgkmcnt(0)
	s_nop 0
	v_mfma_f32_32x32x16_bf16 v[4:19], v[52:55], v[44:47], v[4:19]
	ds_read_b64_tr_b16 v[44:45],v190 offset:4096
	ds_read_b64_tr_b16 v[46:47],v190 offset:4608
	v_mfma_f32_32x32x16_bf16 v[4:19], v[56:59], v[48:51], v[4:19]
	ds_read_b64_tr_b16 v[48:49],v190 offset:5120
	ds_read_b64_tr_b16 v[50:51],v190 offset:5632
	v_mfma_f32_32x32x16_bf16 v[4:19], v[36:39], v[60:63], v[4:19]
	ds_read_b64_tr_b16 v[60:61],v190 offset:6144
	ds_read_b64_tr_b16 v[62:63],v190 offset:6656
	v_mfma_f32_32x32x16_bf16 v[4:19], v[40:43], v[64:67], v[4:19]
	ds_read_b64_tr_b16 v[64:65],v190 offset:7168
	ds_read_b64_tr_b16 v[66:67],v190 offset:7680
	s_waitcnt lgkmcnt(0)
	v_mfma_f32_32x32x16_bf16 v[20:35], v[52:55], v[44:47], v[20:35]
	v_cmp_gt_u32_e32 vcc, 32, v184
	v_mfma_f32_32x32x16_bf16 v[20:35], v[56:59], v[48:51], v[20:35]
	v_mfma_f32_32x32x16_bf16 v[20:35], v[36:39], v[60:63], v[20:35]
	v_mov_b32_e32 v36, v2
	s_nop 1
	v_permlane32_swap_b32_e32 v2, v36
	v_mfma_f32_32x32x16_bf16 v[20:35], v[40:43], v[64:67], v[20:35]
	s_and_saveexec_b64 s[8:9], vcc
	s_cbranch_execz .LBB0_470
	v_lshl_add_u32 v37, v185, 2, s12
	v_add_f32_e32 v2, v2, v36
	ds_write_b32 v37, v2 offset:49280
	s_branch .LBB0_470
